# c34 + P8 gate epilogue VALU trim (canonicalising v_max dropped, alignbit+and folded); bit-identical
# speedup vs baseline: 1.0248x; 1.0012x over previous
; __device__ __forceinline__ unsigned cvt_pk_bf16(float lo, float hi) { unsigned r; asm volatile("v_cvt_pk_bf16_f32 %0, %1, %2" : "=v"(r) : "v"(lo), "v"(hi)); return r; }
;     __device__ __forceinline__ void operator()(f32x4 (&acc)[2][2][4][2], const Unit& u, int wr, int wc, int fr, int fq) const {
;     ...
;                         const unsigned long long wb = wbv[m][bj][n];
;                         f32x4 eb;
;                         eb[0] = __expf(-fmaxf(__uint_as_float((unsigned)(wb & 0xffffull) << 16), -60.f)); eb[1] = __expf(-fmaxf(__uint_as_float((unsigned)((wb >> 16) & 0xffffull) << 16), -60.f));
;                         eb[2] = __expf(-fmaxf(__uint_as_float((unsigned)((wb >> 32) & 0xffffull) << 16), -60.f)); eb[3] = __expf(-fmaxf(__uint_as_float((unsigned)((wb >> 48) & 0xffffull) << 16), -60.f));
;                         if (u.kh == 0) {
;                             const unsigned long long wa = wav[m][bj][n];
;                             f32x4 ea;
;                             ea[0] = __expf(-__uint_as_float((unsigned)(wa & 0xffffull) << 16)); ea[1] = __expf(-__uint_as_float((unsigned)((wa >> 16) & 0xffffull) << 16));
;                             ea[2] = __expf(-__uint_as_float((unsigned)((wa >> 32) & 0xffffull) << 16)); ea[3] = __expf(-__uint_as_float((unsigned)((wa >> 48) & 0xffffull) << 16));
; #pragma unroll
;                             for (int e_ = 0; e_ < 4; ++e_) acc[ai][bj][m][n][e_] *= (1.0f + eb[e_]) * __builtin_amdgcn_rcpf(1.0f + ea[e_]);
;                         } else {
;                             f32x4 o;
; #pragma unroll
;                             for (int e_ = 0; e_ < 4; ++e_) o[e_] = acc[ai][bj][m][n][e_] * __builtin_amdgcn_rcpf(1.0f + eb[e_]);
;                             *(unsigned long long*)(merged + off + bj * HALF + 16 * n) = (unsigned long long)cvt_pk_bf16(o[0], o[1]) | ((unsigned long long)cvt_pk_bf16(o[2], o[3]) << 32);
.LBB0_931:
	s_waitcnt vmcnt(0)
	v_lshlrev_b32_e32 v1, 16, v212
	v_max_f32_e32 v1, 0xc2700000, v1
	v_mul_f32_e32 v1, 0xbfb8aa3b, v1
	v_exp_f32_e32 v218, v1
	v_and_b32_e32 v1, 0xffff0000, v212
	v_max_f32_e32 v1, 0xc2700000, v1
	v_mul_f32_e32 v1, 0xbfb8aa3b, v1
	v_exp_f32_e32 v219, v1
	v_lshlrev_b32_e32 v1, 16, v213
	v_max_f32_e32 v1, 0xc2700000, v1
	v_mul_f32_e32 v1, 0xbfb8aa3b, v1
	v_exp_f32_e32 v220, v1
	v_and_b32_e32 v1, 0xffff0000, v213
	v_max_f32_e32 v1, 0xc2700000, v1
	v_mul_f32_e32 v1, 0xbfb8aa3b, v1
	v_exp_f32_e32 v221, v1
	v_or_b32_e32 v2, s21, v225
	v_lshlrev_b64 v[228:229], 11, v[144:145]
	v_ashrrev_i32_e32 v3, 31, v2
	v_cndmask_b32_e64 v1, 0, 1, s[38:39]
	v_lshl_add_u64 v[212:213], s[14:15], 0, v[228:229]
	s_mov_b64 s[42:43], -1
	v_cmp_ne_u32_e64 s[4:5], 1, v1
	s_andn2_b64 vcc, exec, s[38:39]
	v_lshl_add_u64 v[212:213], v[2:3], 1, v[212:213]
	s_cbranch_vccnz .LBB0_933
	v_add_f32_e32 v1, 1.0, v218
	v_add_f32_e32 v145, 1.0, v219
	v_add_f32_e32 v222, 1.0, v220
	v_add_f32_e32 v227, 1.0, v221
	v_rcp_f32_e32 v1, v1
	v_rcp_f32_e32 v145, v145
	v_rcp_f32_e32 v222, v222
	v_rcp_f32_e32 v227, v227
	s_mov_b64 s[42:43], 0
	v_mul_f32_e32 v1, v128, v1
	v_mul_f32_e32 v145, v129, v145
	v_mul_f32_e32 v222, v130, v222
	v_mul_f32_e32 v227, v131, v227
	v_cvt_pk_bf16_f32 v228, v1, v145
	v_cvt_pk_bf16_f32 v229, v222, v227
	v_and_b32_e32 v244, 48, v254
	v_mov_b32_e32 v245, 0
	v_lshrrev_b32_e32 v244, 1, v244
	v_mov_b32_e32 v240, v228
	v_mov_b32_e32 v241, v229

; __device__ __forceinline__ unsigned cvt_pk_bf16(float lo, float hi) { unsigned r; asm volatile("v_cvt_pk_bf16_f32 %0, %1, %2" : "=v"(r) : "v"(lo), "v"(hi)); return r; }
;     __device__ __forceinline__ void operator()(f32x4 (&acc)[2][2][4][2], const Unit& u, int wr, int wc, int fr, int fq) const {
;     ...
;                         const unsigned long long wb = wbv[m][bj][n];
;                         f32x4 eb;
;                         eb[0] = __expf(-fmaxf(__uint_as_float((unsigned)(wb & 0xffffull) << 16), -60.f)); eb[1] = __expf(-fmaxf(__uint_as_float((unsigned)((wb >> 16) & 0xffffull) << 16), -60.f));
;                         eb[2] = __expf(-fmaxf(__uint_as_float((unsigned)((wb >> 32) & 0xffffull) << 16), -60.f)); eb[3] = __expf(-fmaxf(__uint_as_float((unsigned)((wb >> 48) & 0xffffull) << 16), -60.f));
;                         if (u.kh == 0) {
;                             const unsigned long long wa = wav[m][bj][n];
;                             f32x4 ea;
;                             ea[0] = __expf(-__uint_as_float((unsigned)(wa & 0xffffull) << 16)); ea[1] = __expf(-__uint_as_float((unsigned)((wa >> 16) & 0xffffull) << 16));
;                             ea[2] = __expf(-__uint_as_float((unsigned)((wa >> 32) & 0xffffull) << 16)); ea[3] = __expf(-__uint_as_float((unsigned)((wa >> 48) & 0xffffull) << 16));
; #pragma unroll
;                             for (int e_ = 0; e_ < 4; ++e_) acc[ai][bj][m][n][e_] *= (1.0f + eb[e_]) * __builtin_amdgcn_rcpf(1.0f + ea[e_]);
;                         } else {
;                             f32x4 o;
; #pragma unroll
;                             for (int e_ = 0; e_ < 4; ++e_) o[e_] = acc[ai][bj][m][n][e_] * __builtin_amdgcn_rcpf(1.0f + eb[e_]);
;                             *(unsigned long long*)(merged + off + bj * HALF + 16 * n) = (unsigned long long)cvt_pk_bf16(o[0], o[1]) | ((unsigned long long)cvt_pk_bf16(o[2], o[3]) << 32);
.LBB0_935:
	v_lshlrev_b32_e32 v1, 16, v214
	v_max_f32_e32 v1, 0xc2700000, v1
	v_mul_f32_e32 v1, 0xbfb8aa3b, v1
	v_exp_f32_e32 v216, v1
	v_and_b32_e32 v1, 0xffff0000, v214
	v_max_f32_e32 v1, 0xc2700000, v1
	v_mul_f32_e32 v1, 0xbfb8aa3b, v1
	v_exp_f32_e32 v217, v1
	v_lshlrev_b32_e32 v1, 16, v215
	v_max_f32_e32 v1, 0xc2700000, v1
	v_mul_f32_e32 v1, 0xbfb8aa3b, v1
	v_exp_f32_e32 v214, v1
	v_and_b32_e32 v1, 0xffff0000, v215
	v_max_f32_e32 v1, 0xc2700000, v1
	v_mul_f32_e32 v1, 0xbfb8aa3b, v1
	v_exp_f32_e32 v215, v1
	s_and_b64 vcc, exec, s[4:5]
	s_mov_b64 s[38:39], -1
	s_cbranch_vccnz .LBB0_937
	v_add_f32_e32 v219, 1.0, v215
	v_add_f32_e32 v1, 1.0, v216
	v_add_f32_e32 v145, 1.0, v217
	v_add_f32_e32 v218, 1.0, v214
	v_rcp_f32_e32 v219, v219
	v_rcp_f32_e32 v1, v1
	v_rcp_f32_e32 v145, v145
	v_rcp_f32_e32 v218, v218
	v_mul_f32_e32 v219, v127, v219
	s_mov_b64 s[38:39], 0
	v_mul_f32_e32 v1, v124, v1
	v_mul_f32_e32 v145, v125, v145
	v_mul_f32_e32 v220, v126, v218
	v_cvt_pk_bf16_f32 v218, v1, v145
	v_cvt_pk_bf16_f32 v219, v220, v219
	v_mov_b32_e32 v242, v218
	v_mov_b32_e32 v243, v219
	v_lshl_add_u64 v[246:247], v[212:213], 0, v[244:245]
	s_nop 0
	v_permlane32_swap_b32_e32 v240, v242
	v_permlane32_swap_b32_e32 v241, v243
	s_nop 0
	v_permlane16_swap_b32_e32 v240, v242
	v_permlane16_swap_b32_e32 v241, v243
	s_nop 1
	global_store_dwordx4 v[246:247], v[240:243], off

; __device__ __forceinline__ unsigned cvt_pk_bf16(float lo, float hi) { unsigned r; asm volatile("v_cvt_pk_bf16_f32 %0, %1, %2" : "=v"(r) : "v"(lo), "v"(hi)); return r; }
;     __device__ __forceinline__ void operator()(f32x4 (&acc)[2][2][4][2], const Unit& u, int wr, int wc, int fr, int fq) const {
;     ...
;                         const unsigned long long wb = wbv[m][bj][n];
;                         f32x4 eb;
;                         eb[0] = __expf(-fmaxf(__uint_as_float((unsigned)(wb & 0xffffull) << 16), -60.f)); eb[1] = __expf(-fmaxf(__uint_as_float((unsigned)((wb >> 16) & 0xffffull) << 16), -60.f));
;                         eb[2] = __expf(-fmaxf(__uint_as_float((unsigned)((wb >> 32) & 0xffffull) << 16), -60.f)); eb[3] = __expf(-fmaxf(__uint_as_float((unsigned)((wb >> 48) & 0xffffull) << 16), -60.f));
;                         if (u.kh == 0) {
;                             const unsigned long long wa = wav[m][bj][n];
;                             f32x4 ea;
;                             ea[0] = __expf(-__uint_as_float((unsigned)(wa & 0xffffull) << 16)); ea[1] = __expf(-__uint_as_float((unsigned)((wa >> 16) & 0xffffull) << 16));
;                             ea[2] = __expf(-__uint_as_float((unsigned)((wa >> 32) & 0xffffull) << 16)); ea[3] = __expf(-__uint_as_float((unsigned)((wa >> 48) & 0xffffull) << 16));
; #pragma unroll
;                             for (int e_ = 0; e_ < 4; ++e_) acc[ai][bj][m][n][e_] *= (1.0f + eb[e_]) * __builtin_amdgcn_rcpf(1.0f + ea[e_]);
;                         } else {
;                             f32x4 o;
; #pragma unroll
;                             for (int e_ = 0; e_ < 4; ++e_) o[e_] = acc[ai][bj][m][n][e_] * __builtin_amdgcn_rcpf(1.0f + eb[e_]);
;                             *(unsigned long long*)(merged + off + bj * HALF + 16 * n) = (unsigned long long)cvt_pk_bf16(o[0], o[1]) | ((unsigned long long)cvt_pk_bf16(o[2], o[3]) << 32);
.LBB0_939:
	v_lshlrev_b32_e32 v1, 16, v208
	v_max_f32_e32 v1, 0xc2700000, v1
	v_mul_f32_e32 v1, 0xbfb8aa3b, v1
	v_exp_f32_e32 v210, v1
	v_and_b32_e32 v1, 0xffff0000, v208
	v_max_f32_e32 v1, 0xc2700000, v1
	v_mul_f32_e32 v1, 0xbfb8aa3b, v1
	v_exp_f32_e32 v211, v1
	v_lshlrev_b32_e32 v1, 16, v209
	v_max_f32_e32 v1, 0xc2700000, v1
	v_mul_f32_e32 v1, 0xbfb8aa3b, v1
	v_exp_f32_e32 v208, v1
	v_and_b32_e32 v1, 0xffff0000, v209
	v_max_f32_e32 v1, 0xc2700000, v1
	v_mul_f32_e32 v1, 0xbfb8aa3b, v1
	v_exp_f32_e32 v209, v1
	s_and_b64 vcc, exec, s[4:5]
	s_mov_b64 s[38:39], -1
	s_cbranch_vccnz .LBB0_941
	v_add_f32_e32 v215, 1.0, v209
	v_add_f32_e32 v1, 1.0, v210
	v_add_f32_e32 v145, 1.0, v211
	v_add_f32_e32 v214, 1.0, v208
	v_rcp_f32_e32 v215, v215
	v_rcp_f32_e32 v1, v1
	v_rcp_f32_e32 v145, v145
	v_rcp_f32_e32 v214, v214
	v_mul_f32_e32 v215, v99, v215
	s_mov_b64 s[38:39], 0
	v_mul_f32_e32 v1, v96, v1
	v_mul_f32_e32 v145, v97, v145
	v_mul_f32_e32 v216, v98, v214
	v_cvt_pk_bf16_f32 v214, v1, v145
	v_cvt_pk_bf16_f32 v215, v216, v215
	v_mov_b32_e32 v240, v214
	v_mov_b32_e32 v241, v215

; __device__ __forceinline__ unsigned cvt_pk_bf16(float lo, float hi) { unsigned r; asm volatile("v_cvt_pk_bf16_f32 %0, %1, %2" : "=v"(r) : "v"(lo), "v"(hi)); return r; }
;     __device__ __forceinline__ void operator()(f32x4 (&acc)[2][2][4][2], const Unit& u, int wr, int wc, int fr, int fq) const {
;     ...
;                         const unsigned long long wb = wbv[m][bj][n];
;                         f32x4 eb;
;                         eb[0] = __expf(-fmaxf(__uint_as_float((unsigned)(wb & 0xffffull) << 16), -60.f)); eb[1] = __expf(-fmaxf(__uint_as_float((unsigned)((wb >> 16) & 0xffffull) << 16), -60.f));
;                         eb[2] = __expf(-fmaxf(__uint_as_float((unsigned)((wb >> 32) & 0xffffull) << 16), -60.f)); eb[3] = __expf(-fmaxf(__uint_as_float((unsigned)((wb >> 48) & 0xffffull) << 16), -60.f));
;                         if (u.kh == 0) {
;                             const unsigned long long wa = wav[m][bj][n];
;                             f32x4 ea;
;                             ea[0] = __expf(-__uint_as_float((unsigned)(wa & 0xffffull) << 16)); ea[1] = __expf(-__uint_as_float((unsigned)((wa >> 16) & 0xffffull) << 16));
;                             ea[2] = __expf(-__uint_as_float((unsigned)((wa >> 32) & 0xffffull) << 16)); ea[3] = __expf(-__uint_as_float((unsigned)((wa >> 48) & 0xffffull) << 16));
; #pragma unroll
;                             for (int e_ = 0; e_ < 4; ++e_) acc[ai][bj][m][n][e_] *= (1.0f + eb[e_]) * __builtin_amdgcn_rcpf(1.0f + ea[e_]);
;                         } else {
;                             f32x4 o;
; #pragma unroll
;                             for (int e_ = 0; e_ < 4; ++e_) o[e_] = acc[ai][bj][m][n][e_] * __builtin_amdgcn_rcpf(1.0f + eb[e_]);
;                             *(unsigned long long*)(merged + off + bj * HALF + 16 * n) = (unsigned long long)cvt_pk_bf16(o[0], o[1]) | ((unsigned long long)cvt_pk_bf16(o[2], o[3]) << 32);
.LBB0_943:
	v_lshlrev_b32_e32 v1, 16, v204
	v_max_f32_e32 v1, 0xc2700000, v1
	v_mul_f32_e32 v1, 0xbfb8aa3b, v1
	v_exp_f32_e32 v206, v1
	v_and_b32_e32 v1, 0xffff0000, v204
	v_max_f32_e32 v1, 0xc2700000, v1
	v_mul_f32_e32 v1, 0xbfb8aa3b, v1
	v_exp_f32_e32 v207, v1
	v_lshlrev_b32_e32 v1, 16, v205
	v_max_f32_e32 v1, 0xc2700000, v1
	v_mul_f32_e32 v1, 0xbfb8aa3b, v1
	v_exp_f32_e32 v204, v1
	v_and_b32_e32 v1, 0xffff0000, v205
	v_max_f32_e32 v1, 0xc2700000, v1
	v_mul_f32_e32 v1, 0xbfb8aa3b, v1
	v_exp_f32_e32 v205, v1
	s_and_b64 vcc, exec, s[4:5]
	s_mov_b64 s[38:39], -1
	s_cbranch_vccnz .LBB0_945
	v_add_f32_e32 v209, 1.0, v205
	v_add_f32_e32 v1, 1.0, v206
	v_add_f32_e32 v145, 1.0, v207
	v_add_f32_e32 v208, 1.0, v204
	v_rcp_f32_e32 v209, v209
	v_rcp_f32_e32 v1, v1
	v_rcp_f32_e32 v145, v145
	v_rcp_f32_e32 v208, v208
	v_mul_f32_e32 v209, v95, v209
	s_mov_b64 s[38:39], 0
	v_mul_f32_e32 v1, v92, v1
	v_mul_f32_e32 v145, v93, v145
	v_mul_f32_e32 v210, v94, v208
	v_cvt_pk_bf16_f32 v208, v1, v145
	v_cvt_pk_bf16_f32 v209, v210, v209
	v_mov_b32_e32 v242, v208
	v_mov_b32_e32 v243, v209
	v_lshl_add_u64 v[246:247], v[212:213], 0, v[244:245]
	s_nop 0
	v_permlane32_swap_b32_e32 v240, v242
	v_permlane32_swap_b32_e32 v241, v243
	s_nop 0
	v_permlane16_swap_b32_e32 v240, v242
	v_permlane16_swap_b32_e32 v241, v243
	s_nop 1
	global_store_dwordx4 v[246:247], v[240:243], off offset:256

; __device__ __forceinline__ unsigned cvt_pk_bf16(float lo, float hi) { unsigned r; asm volatile("v_cvt_pk_bf16_f32 %0, %1, %2" : "=v"(r) : "v"(lo), "v"(hi)); return r; }
;     __device__ __forceinline__ void operator()(f32x4 (&acc)[2][2][4][2], const Unit& u, int wr, int wc, int fr, int fq) const {
;     ...
;                         const unsigned long long wb = wbv[m][bj][n];
;                         f32x4 eb;
;                         eb[0] = __expf(-fmaxf(__uint_as_float((unsigned)(wb & 0xffffull) << 16), -60.f)); eb[1] = __expf(-fmaxf(__uint_as_float((unsigned)((wb >> 16) & 0xffffull) << 16), -60.f));
;                         eb[2] = __expf(-fmaxf(__uint_as_float((unsigned)((wb >> 32) & 0xffffull) << 16), -60.f)); eb[3] = __expf(-fmaxf(__uint_as_float((unsigned)((wb >> 48) & 0xffffull) << 16), -60.f));
;                         if (u.kh == 0) {
;                             const unsigned long long wa = wav[m][bj][n];
;                             f32x4 ea;
;                             ea[0] = __expf(-__uint_as_float((unsigned)(wa & 0xffffull) << 16)); ea[1] = __expf(-__uint_as_float((unsigned)((wa >> 16) & 0xffffull) << 16));
;                             ea[2] = __expf(-__uint_as_float((unsigned)((wa >> 32) & 0xffffull) << 16)); ea[3] = __expf(-__uint_as_float((unsigned)((wa >> 48) & 0xffffull) << 16));
; #pragma unroll
;                             for (int e_ = 0; e_ < 4; ++e_) acc[ai][bj][m][n][e_] *= (1.0f + eb[e_]) * __builtin_amdgcn_rcpf(1.0f + ea[e_]);
;                         } else {
;                             f32x4 o;
; #pragma unroll
;                             for (int e_ = 0; e_ < 4; ++e_) o[e_] = acc[ai][bj][m][n][e_] * __builtin_amdgcn_rcpf(1.0f + eb[e_]);
;                             *(unsigned long long*)(merged + off + bj * HALF + 16 * n) = (unsigned long long)cvt_pk_bf16(o[0], o[1]) | ((unsigned long long)cvt_pk_bf16(o[2], o[3]) << 32);
.LBB0_947:
	v_lshlrev_b32_e32 v1, 16, v198
	v_max_f32_e32 v1, 0xc2700000, v1
	v_mul_f32_e32 v1, 0xbfb8aa3b, v1
	v_lshlrev_b64 v[204:205], 11, v[200:201]
	v_exp_f32_e32 v200, v1
	v_and_b32_e32 v1, 0xffff0000, v198
	v_max_f32_e32 v1, 0xc2700000, v1
	v_mul_f32_e32 v1, 0xbfb8aa3b, v1
	v_exp_f32_e32 v201, v1
	v_lshlrev_b32_e32 v1, 16, v199
	v_max_f32_e32 v1, 0xc2700000, v1
	v_mul_f32_e32 v1, 0xbfb8aa3b, v1
	v_exp_f32_e32 v202, v1
	v_and_b32_e32 v1, 0xffff0000, v199
	v_max_f32_e32 v1, 0xc2700000, v1
	v_mul_f32_e32 v1, 0xbfb8aa3b, v1
	v_exp_f32_e32 v203, v1
	v_lshl_add_u64 v[198:199], s[14:15], 0, v[204:205]
	s_mov_b64 s[38:39], -1
	s_and_b64 vcc, exec, s[4:5]
	v_lshl_add_u64 v[198:199], v[2:3], 1, v[198:199]
	s_cbranch_vccnz .LBB0_949
	v_add_f32_e32 v205, 1.0, v203
	v_add_f32_e32 v1, 1.0, v200
	v_add_f32_e32 v145, 1.0, v201
	v_add_f32_e32 v204, 1.0, v202
	v_rcp_f32_e32 v205, v205
	v_rcp_f32_e32 v1, v1
	v_rcp_f32_e32 v145, v145
	v_rcp_f32_e32 v204, v204
	v_mul_f32_e32 v205, v123, v205
	s_mov_b64 s[38:39], 0
	v_mul_f32_e32 v1, v120, v1
	v_mul_f32_e32 v145, v121, v145
	v_mul_f32_e32 v206, v122, v204
	v_cvt_pk_bf16_f32 v204, v1, v145
	v_cvt_pk_bf16_f32 v205, v206, v205
	v_and_b32_e32 v244, 48, v254
	v_mov_b32_e32 v245, 0
	v_lshrrev_b32_e32 v244, 1, v244
	v_mov_b32_e32 v240, v204
	v_mov_b32_e32 v241, v205

; __device__ __forceinline__ unsigned cvt_pk_bf16(float lo, float hi) { unsigned r; asm volatile("v_cvt_pk_bf16_f32 %0, %1, %2" : "=v"(r) : "v"(lo), "v"(hi)); return r; }
;     __device__ __forceinline__ void operator()(f32x4 (&acc)[2][2][4][2], const Unit& u, int wr, int wc, int fr, int fq) const {
;     ...
;                         const unsigned long long wb = wbv[m][bj][n];
;                         f32x4 eb;
;                         eb[0] = __expf(-fmaxf(__uint_as_float((unsigned)(wb & 0xffffull) << 16), -60.f)); eb[1] = __expf(-fmaxf(__uint_as_float((unsigned)((wb >> 16) & 0xffffull) << 16), -60.f));
;                         eb[2] = __expf(-fmaxf(__uint_as_float((unsigned)((wb >> 32) & 0xffffull) << 16), -60.f)); eb[3] = __expf(-fmaxf(__uint_as_float((unsigned)((wb >> 48) & 0xffffull) << 16), -60.f));
;                         if (u.kh == 0) {
;                             const unsigned long long wa = wav[m][bj][n];
;                             f32x4 ea;
;                             ea[0] = __expf(-__uint_as_float((unsigned)(wa & 0xffffull) << 16)); ea[1] = __expf(-__uint_as_float((unsigned)((wa >> 16) & 0xffffull) << 16));
;                             ea[2] = __expf(-__uint_as_float((unsigned)((wa >> 32) & 0xffffull) << 16)); ea[3] = __expf(-__uint_as_float((unsigned)((wa >> 48) & 0xffffull) << 16));
; #pragma unroll
;                             for (int e_ = 0; e_ < 4; ++e_) acc[ai][bj][m][n][e_] *= (1.0f + eb[e_]) * __builtin_amdgcn_rcpf(1.0f + ea[e_]);
;                         } else {
;                             f32x4 o;
; #pragma unroll
;                             for (int e_ = 0; e_ < 4; ++e_) o[e_] = acc[ai][bj][m][n][e_] * __builtin_amdgcn_rcpf(1.0f + eb[e_]);
;                             *(unsigned long long*)(merged + off + bj * HALF + 16 * n) = (unsigned long long)cvt_pk_bf16(o[0], o[1]) | ((unsigned long long)cvt_pk_bf16(o[2], o[3]) << 32);
.LBB0_951:
	v_lshlrev_b32_e32 v1, 16, v194
	v_max_f32_e32 v1, 0xc2700000, v1
	v_mul_f32_e32 v1, 0xbfb8aa3b, v1
	v_exp_f32_e32 v196, v1
	v_and_b32_e32 v1, 0xffff0000, v194
	v_max_f32_e32 v1, 0xc2700000, v1
	v_mul_f32_e32 v1, 0xbfb8aa3b, v1
	v_exp_f32_e32 v197, v1
	v_lshlrev_b32_e32 v1, 16, v195
	v_max_f32_e32 v1, 0xc2700000, v1
	v_mul_f32_e32 v1, 0xbfb8aa3b, v1
	v_exp_f32_e32 v194, v1
	v_and_b32_e32 v1, 0xffff0000, v195
	v_max_f32_e32 v1, 0xc2700000, v1
	v_mul_f32_e32 v1, 0xbfb8aa3b, v1
	v_exp_f32_e32 v195, v1
	s_and_b64 vcc, exec, s[4:5]
	s_mov_b64 s[38:39], -1
	s_cbranch_vccnz .LBB0_953
	v_add_f32_e32 v201, 1.0, v195
	v_add_f32_e32 v1, 1.0, v196
	v_add_f32_e32 v145, 1.0, v197
	v_add_f32_e32 v200, 1.0, v194
	v_rcp_f32_e32 v201, v201
	v_rcp_f32_e32 v1, v1
	v_rcp_f32_e32 v145, v145
	v_rcp_f32_e32 v200, v200
	v_mul_f32_e32 v201, v119, v201
	s_mov_b64 s[38:39], 0
	v_mul_f32_e32 v1, v116, v1
	v_mul_f32_e32 v145, v117, v145
	v_mul_f32_e32 v202, v118, v200
	v_cvt_pk_bf16_f32 v200, v1, v145
	v_cvt_pk_bf16_f32 v201, v202, v201
	v_mov_b32_e32 v242, v200
	v_mov_b32_e32 v243, v201
	v_lshl_add_u64 v[246:247], v[198:199], 0, v[244:245]
	s_nop 0
	v_permlane32_swap_b32_e32 v240, v242
	v_permlane32_swap_b32_e32 v241, v243
	s_nop 0
	v_permlane16_swap_b32_e32 v240, v242
	v_permlane16_swap_b32_e32 v241, v243
	s_nop 1
	global_store_dwordx4 v[246:247], v[240:243], off

; __device__ __forceinline__ unsigned cvt_pk_bf16(float lo, float hi) { unsigned r; asm volatile("v_cvt_pk_bf16_f32 %0, %1, %2" : "=v"(r) : "v"(lo), "v"(hi)); return r; }
;     __device__ __forceinline__ void operator()(f32x4 (&acc)[2][2][4][2], const Unit& u, int wr, int wc, int fr, int fq) const {
;     ...
;                         const unsigned long long wb = wbv[m][bj][n];
;                         f32x4 eb;
;                         eb[0] = __expf(-fmaxf(__uint_as_float((unsigned)(wb & 0xffffull) << 16), -60.f)); eb[1] = __expf(-fmaxf(__uint_as_float((unsigned)((wb >> 16) & 0xffffull) << 16), -60.f));
;                         eb[2] = __expf(-fmaxf(__uint_as_float((unsigned)((wb >> 32) & 0xffffull) << 16), -60.f)); eb[3] = __expf(-fmaxf(__uint_as_float((unsigned)((wb >> 48) & 0xffffull) << 16), -60.f));
;                         if (u.kh == 0) {
;                             const unsigned long long wa = wav[m][bj][n];
;                             f32x4 ea;
;                             ea[0] = __expf(-__uint_as_float((unsigned)(wa & 0xffffull) << 16)); ea[1] = __expf(-__uint_as_float((unsigned)((wa >> 16) & 0xffffull) << 16));
;                             ea[2] = __expf(-__uint_as_float((unsigned)((wa >> 32) & 0xffffull) << 16)); ea[3] = __expf(-__uint_as_float((unsigned)((wa >> 48) & 0xffffull) << 16));
; #pragma unroll
;                             for (int e_ = 0; e_ < 4; ++e_) acc[ai][bj][m][n][e_] *= (1.0f + eb[e_]) * __builtin_amdgcn_rcpf(1.0f + ea[e_]);
;                         } else {
;                             f32x4 o;
; #pragma unroll
;                             for (int e_ = 0; e_ < 4; ++e_) o[e_] = acc[ai][bj][m][n][e_] * __builtin_amdgcn_rcpf(1.0f + eb[e_]);
;                             *(unsigned long long*)(merged + off + bj * HALF + 16 * n) = (unsigned long long)cvt_pk_bf16(o[0], o[1]) | ((unsigned long long)cvt_pk_bf16(o[2], o[3]) << 32);
.LBB0_955:
	v_lshlrev_b32_e32 v1, 16, v190
	v_max_f32_e32 v1, 0xc2700000, v1
	v_mul_f32_e32 v1, 0xbfb8aa3b, v1
	v_exp_f32_e32 v192, v1
	v_and_b32_e32 v1, 0xffff0000, v190
	v_max_f32_e32 v1, 0xc2700000, v1
	v_mul_f32_e32 v1, 0xbfb8aa3b, v1
	v_exp_f32_e32 v193, v1
	v_lshlrev_b32_e32 v1, 16, v191
	v_max_f32_e32 v1, 0xc2700000, v1
	v_mul_f32_e32 v1, 0xbfb8aa3b, v1
	v_exp_f32_e32 v190, v1
	v_and_b32_e32 v1, 0xffff0000, v191
	v_max_f32_e32 v1, 0xc2700000, v1
	v_mul_f32_e32 v1, 0xbfb8aa3b, v1
	v_exp_f32_e32 v191, v1
	s_and_b64 vcc, exec, s[4:5]
	s_mov_b64 s[38:39], -1
	s_cbranch_vccnz .LBB0_957
	v_add_f32_e32 v195, 1.0, v191
	v_add_f32_e32 v1, 1.0, v192
	v_add_f32_e32 v145, 1.0, v193
	v_add_f32_e32 v194, 1.0, v190
	v_rcp_f32_e32 v195, v195
	v_rcp_f32_e32 v1, v1
	v_rcp_f32_e32 v145, v145
	v_rcp_f32_e32 v194, v194
	v_mul_f32_e32 v195, v91, v195
	s_mov_b64 s[38:39], 0
	v_mul_f32_e32 v1, v88, v1
	v_mul_f32_e32 v145, v89, v145
	v_mul_f32_e32 v196, v90, v194
	v_cvt_pk_bf16_f32 v194, v1, v145
	v_cvt_pk_bf16_f32 v195, v196, v195
	v_mov_b32_e32 v240, v194
	v_mov_b32_e32 v241, v195

; __device__ __forceinline__ unsigned cvt_pk_bf16(float lo, float hi) { unsigned r; asm volatile("v_cvt_pk_bf16_f32 %0, %1, %2" : "=v"(r) : "v"(lo), "v"(hi)); return r; }
;     __device__ __forceinline__ void operator()(f32x4 (&acc)[2][2][4][2], const Unit& u, int wr, int wc, int fr, int fq) const {
;     ...
;                         const unsigned long long wb = wbv[m][bj][n];
;                         f32x4 eb;
;                         eb[0] = __expf(-fmaxf(__uint_as_float((unsigned)(wb & 0xffffull) << 16), -60.f)); eb[1] = __expf(-fmaxf(__uint_as_float((unsigned)((wb >> 16) & 0xffffull) << 16), -60.f));
;                         eb[2] = __expf(-fmaxf(__uint_as_float((unsigned)((wb >> 32) & 0xffffull) << 16), -60.f)); eb[3] = __expf(-fmaxf(__uint_as_float((unsigned)((wb >> 48) & 0xffffull) << 16), -60.f));
;                         if (u.kh == 0) {
;                             const unsigned long long wa = wav[m][bj][n];
;                             f32x4 ea;
;                             ea[0] = __expf(-__uint_as_float((unsigned)(wa & 0xffffull) << 16)); ea[1] = __expf(-__uint_as_float((unsigned)((wa >> 16) & 0xffffull) << 16));
;                             ea[2] = __expf(-__uint_as_float((unsigned)((wa >> 32) & 0xffffull) << 16)); ea[3] = __expf(-__uint_as_float((unsigned)((wa >> 48) & 0xffffull) << 16));
; #pragma unroll
;                             for (int e_ = 0; e_ < 4; ++e_) acc[ai][bj][m][n][e_] *= (1.0f + eb[e_]) * __builtin_amdgcn_rcpf(1.0f + ea[e_]);
;                         } else {
;                             f32x4 o;
; #pragma unroll
;                             for (int e_ = 0; e_ < 4; ++e_) o[e_] = acc[ai][bj][m][n][e_] * __builtin_amdgcn_rcpf(1.0f + eb[e_]);
;                             *(unsigned long long*)(merged + off + bj * HALF + 16 * n) = (unsigned long long)cvt_pk_bf16(o[0], o[1]) | ((unsigned long long)cvt_pk_bf16(o[2], o[3]) << 32);
.LBB0_959:
	v_lshlrev_b32_e32 v1, 16, v186
	v_max_f32_e32 v1, 0xc2700000, v1
	v_mul_f32_e32 v1, 0xbfb8aa3b, v1
	v_exp_f32_e32 v188, v1
	v_and_b32_e32 v1, 0xffff0000, v186
	v_max_f32_e32 v1, 0xc2700000, v1
	v_mul_f32_e32 v1, 0xbfb8aa3b, v1
	v_exp_f32_e32 v189, v1
	v_lshlrev_b32_e32 v1, 16, v187
	v_max_f32_e32 v1, 0xc2700000, v1
	v_mul_f32_e32 v1, 0xbfb8aa3b, v1
	v_exp_f32_e32 v186, v1
	v_and_b32_e32 v1, 0xffff0000, v187
	v_max_f32_e32 v1, 0xc2700000, v1
	v_mul_f32_e32 v1, 0xbfb8aa3b, v1
	v_exp_f32_e32 v187, v1
	s_and_b64 vcc, exec, s[4:5]
	s_mov_b64 s[38:39], -1
	s_cbranch_vccnz .LBB0_961
	v_add_f32_e32 v191, 1.0, v187
	v_add_f32_e32 v1, 1.0, v188
	v_add_f32_e32 v145, 1.0, v189
	v_add_f32_e32 v190, 1.0, v186
	v_rcp_f32_e32 v191, v191
	v_rcp_f32_e32 v1, v1
	v_rcp_f32_e32 v145, v145
	v_rcp_f32_e32 v190, v190
	v_mul_f32_e32 v191, v87, v191
	s_mov_b64 s[38:39], 0
	v_mul_f32_e32 v1, v84, v1
	v_mul_f32_e32 v145, v85, v145
	v_mul_f32_e32 v192, v86, v190
	v_cvt_pk_bf16_f32 v190, v1, v145
	v_cvt_pk_bf16_f32 v191, v192, v191
	v_mov_b32_e32 v242, v190
	v_mov_b32_e32 v243, v191
	v_lshl_add_u64 v[246:247], v[198:199], 0, v[244:245]
	s_nop 0
	v_permlane32_swap_b32_e32 v240, v242
	v_permlane32_swap_b32_e32 v241, v243
	s_nop 0
	v_permlane16_swap_b32_e32 v240, v242
	v_permlane16_swap_b32_e32 v241, v243
	s_nop 1
	global_store_dwordx4 v[246:247], v[240:243], off offset:256

; __device__ __forceinline__ unsigned cvt_pk_bf16(float lo, float hi) { unsigned r; asm volatile("v_cvt_pk_bf16_f32 %0, %1, %2" : "=v"(r) : "v"(lo), "v"(hi)); return r; }
;     __device__ __forceinline__ void operator()(f32x4 (&acc)[2][2][4][2], const Unit& u, int wr, int wc, int fr, int fq) const {
;     ...
;                         const unsigned long long wb = wbv[m][bj][n];
;                         f32x4 eb;
;                         eb[0] = __expf(-fmaxf(__uint_as_float((unsigned)(wb & 0xffffull) << 16), -60.f)); eb[1] = __expf(-fmaxf(__uint_as_float((unsigned)((wb >> 16) & 0xffffull) << 16), -60.f));
;                         eb[2] = __expf(-fmaxf(__uint_as_float((unsigned)((wb >> 32) & 0xffffull) << 16), -60.f)); eb[3] = __expf(-fmaxf(__uint_as_float((unsigned)((wb >> 48) & 0xffffull) << 16), -60.f));
;                         if (u.kh == 0) {
;                             const unsigned long long wa = wav[m][bj][n];
;                             f32x4 ea;
;                             ea[0] = __expf(-__uint_as_float((unsigned)(wa & 0xffffull) << 16)); ea[1] = __expf(-__uint_as_float((unsigned)((wa >> 16) & 0xffffull) << 16));
;                             ea[2] = __expf(-__uint_as_float((unsigned)((wa >> 32) & 0xffffull) << 16)); ea[3] = __expf(-__uint_as_float((unsigned)((wa >> 48) & 0xffffull) << 16));
; #pragma unroll
;                             for (int e_ = 0; e_ < 4; ++e_) acc[ai][bj][m][n][e_] *= (1.0f + eb[e_]) * __builtin_amdgcn_rcpf(1.0f + ea[e_]);
;                         } else {
;                             f32x4 o;
; #pragma unroll
;                             for (int e_ = 0; e_ < 4; ++e_) o[e_] = acc[ai][bj][m][n][e_] * __builtin_amdgcn_rcpf(1.0f + eb[e_]);
;                             *(unsigned long long*)(merged + off + bj * HALF + 16 * n) = (unsigned long long)cvt_pk_bf16(o[0], o[1]) | ((unsigned long long)cvt_pk_bf16(o[2], o[3]) << 32);
.LBB0_963:
	v_lshlrev_b32_e32 v1, 16, v180
	v_max_f32_e32 v1, 0xc2700000, v1
	v_mul_f32_e32 v1, 0xbfb8aa3b, v1
	v_lshlrev_b64 v[186:187], 11, v[182:183]
	v_exp_f32_e32 v182, v1
	v_and_b32_e32 v1, 0xffff0000, v180
	v_max_f32_e32 v1, 0xc2700000, v1
	v_mul_f32_e32 v1, 0xbfb8aa3b, v1
	v_exp_f32_e32 v183, v1
	v_lshlrev_b32_e32 v1, 16, v181
	v_max_f32_e32 v1, 0xc2700000, v1
	v_mul_f32_e32 v1, 0xbfb8aa3b, v1
	v_exp_f32_e32 v184, v1
	v_and_b32_e32 v1, 0xffff0000, v181
	v_max_f32_e32 v1, 0xc2700000, v1
	v_mul_f32_e32 v1, 0xbfb8aa3b, v1
	v_exp_f32_e32 v185, v1
	v_lshl_add_u64 v[180:181], s[14:15], 0, v[186:187]
	s_mov_b64 s[38:39], -1
	s_and_b64 vcc, exec, s[4:5]
	v_lshl_add_u64 v[180:181], v[2:3], 1, v[180:181]
	s_cbranch_vccnz .LBB0_965
	v_add_f32_e32 v187, 1.0, v185
	v_add_f32_e32 v1, 1.0, v182
	v_add_f32_e32 v145, 1.0, v183
	v_add_f32_e32 v186, 1.0, v184
	v_rcp_f32_e32 v187, v187
	v_rcp_f32_e32 v1, v1
	v_rcp_f32_e32 v145, v145
	v_rcp_f32_e32 v186, v186
	v_mul_f32_e32 v187, v115, v187
	s_mov_b64 s[38:39], 0
	v_mul_f32_e32 v1, v112, v1
	v_mul_f32_e32 v145, v113, v145
	v_mul_f32_e32 v188, v114, v186
	v_cvt_pk_bf16_f32 v186, v1, v145
	v_cvt_pk_bf16_f32 v187, v188, v187
	v_and_b32_e32 v244, 48, v254
	v_mov_b32_e32 v245, 0
	v_lshrrev_b32_e32 v244, 1, v244
	v_mov_b32_e32 v240, v186
	v_mov_b32_e32 v241, v187

; __device__ __forceinline__ unsigned cvt_pk_bf16(float lo, float hi) { unsigned r; asm volatile("v_cvt_pk_bf16_f32 %0, %1, %2" : "=v"(r) : "v"(lo), "v"(hi)); return r; }
;     __device__ __forceinline__ void operator()(f32x4 (&acc)[2][2][4][2], const Unit& u, int wr, int wc, int fr, int fq) const {
;     ...
;                         const unsigned long long wb = wbv[m][bj][n];
;                         f32x4 eb;
;                         eb[0] = __expf(-fmaxf(__uint_as_float((unsigned)(wb & 0xffffull) << 16), -60.f)); eb[1] = __expf(-fmaxf(__uint_as_float((unsigned)((wb >> 16) & 0xffffull) << 16), -60.f));
;                         eb[2] = __expf(-fmaxf(__uint_as_float((unsigned)((wb >> 32) & 0xffffull) << 16), -60.f)); eb[3] = __expf(-fmaxf(__uint_as_float((unsigned)((wb >> 48) & 0xffffull) << 16), -60.f));
;                         if (u.kh == 0) {
;                             const unsigned long long wa = wav[m][bj][n];
;                             f32x4 ea;
;                             ea[0] = __expf(-__uint_as_float((unsigned)(wa & 0xffffull) << 16)); ea[1] = __expf(-__uint_as_float((unsigned)((wa >> 16) & 0xffffull) << 16));
;                             ea[2] = __expf(-__uint_as_float((unsigned)((wa >> 32) & 0xffffull) << 16)); ea[3] = __expf(-__uint_as_float((unsigned)((wa >> 48) & 0xffffull) << 16));
; #pragma unroll
;                             for (int e_ = 0; e_ < 4; ++e_) acc[ai][bj][m][n][e_] *= (1.0f + eb[e_]) * __builtin_amdgcn_rcpf(1.0f + ea[e_]);
;                         } else {
;                             f32x4 o;
; #pragma unroll
;                             for (int e_ = 0; e_ < 4; ++e_) o[e_] = acc[ai][bj][m][n][e_] * __builtin_amdgcn_rcpf(1.0f + eb[e_]);
;                             *(unsigned long long*)(merged + off + bj * HALF + 16 * n) = (unsigned long long)cvt_pk_bf16(o[0], o[1]) | ((unsigned long long)cvt_pk_bf16(o[2], o[3]) << 32);
.LBB0_967:
	v_lshlrev_b32_e32 v1, 16, v176
	v_max_f32_e32 v1, 0xc2700000, v1
	v_mul_f32_e32 v1, 0xbfb8aa3b, v1
	v_exp_f32_e32 v178, v1
	v_and_b32_e32 v1, 0xffff0000, v176
	v_max_f32_e32 v1, 0xc2700000, v1
	v_mul_f32_e32 v1, 0xbfb8aa3b, v1
	v_exp_f32_e32 v179, v1
	v_lshlrev_b32_e32 v1, 16, v177
	v_max_f32_e32 v1, 0xc2700000, v1
	v_mul_f32_e32 v1, 0xbfb8aa3b, v1
	v_exp_f32_e32 v176, v1
	v_and_b32_e32 v1, 0xffff0000, v177
	v_max_f32_e32 v1, 0xc2700000, v1
	v_mul_f32_e32 v1, 0xbfb8aa3b, v1
	v_exp_f32_e32 v177, v1
	s_and_b64 vcc, exec, s[4:5]
	s_mov_b64 s[38:39], -1
	s_cbranch_vccnz .LBB0_969
	v_add_f32_e32 v183, 1.0, v177
	v_add_f32_e32 v1, 1.0, v178
	v_add_f32_e32 v145, 1.0, v179
	v_add_f32_e32 v182, 1.0, v176
	v_rcp_f32_e32 v183, v183
	v_rcp_f32_e32 v1, v1
	v_rcp_f32_e32 v145, v145
	v_rcp_f32_e32 v182, v182
	v_mul_f32_e32 v183, v111, v183
	s_mov_b64 s[38:39], 0
	v_mul_f32_e32 v1, v108, v1
	v_mul_f32_e32 v145, v109, v145
	v_mul_f32_e32 v184, v110, v182
	v_cvt_pk_bf16_f32 v182, v1, v145
	v_cvt_pk_bf16_f32 v183, v184, v183
	v_mov_b32_e32 v242, v182
	v_mov_b32_e32 v243, v183
	v_lshl_add_u64 v[246:247], v[180:181], 0, v[244:245]
	s_nop 0
	v_permlane32_swap_b32_e32 v240, v242
	v_permlane32_swap_b32_e32 v241, v243
	s_nop 0
	v_permlane16_swap_b32_e32 v240, v242
	v_permlane16_swap_b32_e32 v241, v243
	s_nop 1
	global_store_dwordx4 v[246:247], v[240:243], off

; __device__ __forceinline__ unsigned cvt_pk_bf16(float lo, float hi) { unsigned r; asm volatile("v_cvt_pk_bf16_f32 %0, %1, %2" : "=v"(r) : "v"(lo), "v"(hi)); return r; }
;     __device__ __forceinline__ void operator()(f32x4 (&acc)[2][2][4][2], const Unit& u, int wr, int wc, int fr, int fq) const {
;     ...
;                         const unsigned long long wb = wbv[m][bj][n];
;                         f32x4 eb;
;                         eb[0] = __expf(-fmaxf(__uint_as_float((unsigned)(wb & 0xffffull) << 16), -60.f)); eb[1] = __expf(-fmaxf(__uint_as_float((unsigned)((wb >> 16) & 0xffffull) << 16), -60.f));
;                         eb[2] = __expf(-fmaxf(__uint_as_float((unsigned)((wb >> 32) & 0xffffull) << 16), -60.f)); eb[3] = __expf(-fmaxf(__uint_as_float((unsigned)((wb >> 48) & 0xffffull) << 16), -60.f));
;                         if (u.kh == 0) {
;                             const unsigned long long wa = wav[m][bj][n];
;                             f32x4 ea;
;                             ea[0] = __expf(-__uint_as_float((unsigned)(wa & 0xffffull) << 16)); ea[1] = __expf(-__uint_as_float((unsigned)((wa >> 16) & 0xffffull) << 16));
;                             ea[2] = __expf(-__uint_as_float((unsigned)((wa >> 32) & 0xffffull) << 16)); ea[3] = __expf(-__uint_as_float((unsigned)((wa >> 48) & 0xffffull) << 16));
; #pragma unroll
;                             for (int e_ = 0; e_ < 4; ++e_) acc[ai][bj][m][n][e_] *= (1.0f + eb[e_]) * __builtin_amdgcn_rcpf(1.0f + ea[e_]);
;                         } else {
;                             f32x4 o;
; #pragma unroll
;                             for (int e_ = 0; e_ < 4; ++e_) o[e_] = acc[ai][bj][m][n][e_] * __builtin_amdgcn_rcpf(1.0f + eb[e_]);
;                             *(unsigned long long*)(merged + off + bj * HALF + 16 * n) = (unsigned long long)cvt_pk_bf16(o[0], o[1]) | ((unsigned long long)cvt_pk_bf16(o[2], o[3]) << 32);
.LBB0_971:
	v_lshlrev_b32_e32 v1, 16, v172
	v_max_f32_e32 v1, 0xc2700000, v1
	v_mul_f32_e32 v1, 0xbfb8aa3b, v1
	v_exp_f32_e32 v174, v1
	v_and_b32_e32 v1, 0xffff0000, v172
	v_max_f32_e32 v1, 0xc2700000, v1
	v_mul_f32_e32 v1, 0xbfb8aa3b, v1
	v_exp_f32_e32 v175, v1
	v_lshlrev_b32_e32 v1, 16, v173
	v_max_f32_e32 v1, 0xc2700000, v1
	v_mul_f32_e32 v1, 0xbfb8aa3b, v1
	v_exp_f32_e32 v172, v1
	v_and_b32_e32 v1, 0xffff0000, v173
	v_max_f32_e32 v1, 0xc2700000, v1
	v_mul_f32_e32 v1, 0xbfb8aa3b, v1
	v_exp_f32_e32 v173, v1
	s_and_b64 vcc, exec, s[4:5]
	s_mov_b64 s[38:39], -1
	s_cbranch_vccnz .LBB0_973
	v_add_f32_e32 v177, 1.0, v173
	v_add_f32_e32 v1, 1.0, v174
	v_add_f32_e32 v145, 1.0, v175
	v_add_f32_e32 v176, 1.0, v172
	v_rcp_f32_e32 v177, v177
	v_rcp_f32_e32 v1, v1
	v_rcp_f32_e32 v145, v145
	v_rcp_f32_e32 v176, v176
	v_mul_f32_e32 v177, v83, v177
	s_mov_b64 s[38:39], 0
	v_mul_f32_e32 v1, v80, v1
	v_mul_f32_e32 v145, v81, v145
	v_mul_f32_e32 v178, v82, v176
	v_cvt_pk_bf16_f32 v176, v1, v145
	v_cvt_pk_bf16_f32 v177, v178, v177
	v_mov_b32_e32 v240, v176
	v_mov_b32_e32 v241, v177

; __device__ __forceinline__ unsigned cvt_pk_bf16(float lo, float hi) { unsigned r; asm volatile("v_cvt_pk_bf16_f32 %0, %1, %2" : "=v"(r) : "v"(lo), "v"(hi)); return r; }
;     __device__ __forceinline__ void operator()(f32x4 (&acc)[2][2][4][2], const Unit& u, int wr, int wc, int fr, int fq) const {
;     ...
;                         const unsigned long long wb = wbv[m][bj][n];
;                         f32x4 eb;
;                         eb[0] = __expf(-fmaxf(__uint_as_float((unsigned)(wb & 0xffffull) << 16), -60.f)); eb[1] = __expf(-fmaxf(__uint_as_float((unsigned)((wb >> 16) & 0xffffull) << 16), -60.f));
;                         eb[2] = __expf(-fmaxf(__uint_as_float((unsigned)((wb >> 32) & 0xffffull) << 16), -60.f)); eb[3] = __expf(-fmaxf(__uint_as_float((unsigned)((wb >> 48) & 0xffffull) << 16), -60.f));
;                         if (u.kh == 0) {
;                             const unsigned long long wa = wav[m][bj][n];
;                             f32x4 ea;
;                             ea[0] = __expf(-__uint_as_float((unsigned)(wa & 0xffffull) << 16)); ea[1] = __expf(-__uint_as_float((unsigned)((wa >> 16) & 0xffffull) << 16));
;                             ea[2] = __expf(-__uint_as_float((unsigned)((wa >> 32) & 0xffffull) << 16)); ea[3] = __expf(-__uint_as_float((unsigned)((wa >> 48) & 0xffffull) << 16));
; #pragma unroll
;                             for (int e_ = 0; e_ < 4; ++e_) acc[ai][bj][m][n][e_] *= (1.0f + eb[e_]) * __builtin_amdgcn_rcpf(1.0f + ea[e_]);
;                         } else {
;                             f32x4 o;
; #pragma unroll
;                             for (int e_ = 0; e_ < 4; ++e_) o[e_] = acc[ai][bj][m][n][e_] * __builtin_amdgcn_rcpf(1.0f + eb[e_]);
;                             *(unsigned long long*)(merged + off + bj * HALF + 16 * n) = (unsigned long long)cvt_pk_bf16(o[0], o[1]) | ((unsigned long long)cvt_pk_bf16(o[2], o[3]) << 32);
.LBB0_975:
	v_lshlrev_b32_e32 v1, 16, v168
	v_max_f32_e32 v1, 0xc2700000, v1
	v_mul_f32_e32 v1, 0xbfb8aa3b, v1
	v_exp_f32_e32 v170, v1
	v_and_b32_e32 v1, 0xffff0000, v168
	v_max_f32_e32 v1, 0xc2700000, v1
	v_mul_f32_e32 v1, 0xbfb8aa3b, v1
	v_exp_f32_e32 v171, v1
	v_lshlrev_b32_e32 v1, 16, v169
	v_max_f32_e32 v1, 0xc2700000, v1
	v_mul_f32_e32 v1, 0xbfb8aa3b, v1
	v_exp_f32_e32 v168, v1
	v_and_b32_e32 v1, 0xffff0000, v169
	v_max_f32_e32 v1, 0xc2700000, v1
	v_mul_f32_e32 v1, 0xbfb8aa3b, v1
	v_exp_f32_e32 v169, v1
	s_and_b64 vcc, exec, s[4:5]
	s_mov_b64 s[38:39], -1
	s_cbranch_vccnz .LBB0_977
	v_add_f32_e32 v173, 1.0, v169
	v_add_f32_e32 v1, 1.0, v170
	v_add_f32_e32 v145, 1.0, v171
	v_add_f32_e32 v172, 1.0, v168
	v_rcp_f32_e32 v173, v173
	v_rcp_f32_e32 v1, v1
	v_rcp_f32_e32 v145, v145
	v_rcp_f32_e32 v172, v172
	v_mul_f32_e32 v173, v79, v173
	s_mov_b64 s[38:39], 0
	v_mul_f32_e32 v1, v76, v1
	v_mul_f32_e32 v145, v77, v145
	v_mul_f32_e32 v174, v78, v172
	v_cvt_pk_bf16_f32 v172, v1, v145
	v_cvt_pk_bf16_f32 v173, v174, v173
	v_mov_b32_e32 v242, v172
	v_mov_b32_e32 v243, v173
	v_lshl_add_u64 v[246:247], v[180:181], 0, v[244:245]
	s_nop 0
	v_permlane32_swap_b32_e32 v240, v242
	v_permlane32_swap_b32_e32 v241, v243
	s_nop 0
	v_permlane16_swap_b32_e32 v240, v242
	v_permlane16_swap_b32_e32 v241, v243
	s_nop 1
	global_store_dwordx4 v[246:247], v[240:243], off offset:256

; __device__ __forceinline__ unsigned cvt_pk_bf16(float lo, float hi) { unsigned r; asm volatile("v_cvt_pk_bf16_f32 %0, %1, %2" : "=v"(r) : "v"(lo), "v"(hi)); return r; }
;     __device__ __forceinline__ void operator()(f32x4 (&acc)[2][2][4][2], const Unit& u, int wr, int wc, int fr, int fq) const {
;     ...
;                         const unsigned long long wb = wbv[m][bj][n];
;                         f32x4 eb;
;                         eb[0] = __expf(-fmaxf(__uint_as_float((unsigned)(wb & 0xffffull) << 16), -60.f)); eb[1] = __expf(-fmaxf(__uint_as_float((unsigned)((wb >> 16) & 0xffffull) << 16), -60.f));
;                         eb[2] = __expf(-fmaxf(__uint_as_float((unsigned)((wb >> 32) & 0xffffull) << 16), -60.f)); eb[3] = __expf(-fmaxf(__uint_as_float((unsigned)((wb >> 48) & 0xffffull) << 16), -60.f));
;                         if (u.kh == 0) {
;                             const unsigned long long wa = wav[m][bj][n];
;                             f32x4 ea;
;                             ea[0] = __expf(-__uint_as_float((unsigned)(wa & 0xffffull) << 16)); ea[1] = __expf(-__uint_as_float((unsigned)((wa >> 16) & 0xffffull) << 16));
;                             ea[2] = __expf(-__uint_as_float((unsigned)((wa >> 32) & 0xffffull) << 16)); ea[3] = __expf(-__uint_as_float((unsigned)((wa >> 48) & 0xffffull) << 16));
; #pragma unroll
;                             for (int e_ = 0; e_ < 4; ++e_) acc[ai][bj][m][n][e_] *= (1.0f + eb[e_]) * __builtin_amdgcn_rcpf(1.0f + ea[e_]);
;                         } else {
;                             f32x4 o;
; #pragma unroll
;                             for (int e_ = 0; e_ < 4; ++e_) o[e_] = acc[ai][bj][m][n][e_] * __builtin_amdgcn_rcpf(1.0f + eb[e_]);
;                             *(unsigned long long*)(merged + off + bj * HALF + 16 * n) = (unsigned long long)cvt_pk_bf16(o[0], o[1]) | ((unsigned long long)cvt_pk_bf16(o[2], o[3]) << 32);
.LBB0_979:
	v_lshlrev_b32_e32 v1, 16, v162
	v_max_f32_e32 v1, 0xc2700000, v1
	v_mul_f32_e32 v1, 0xbfb8aa3b, v1
	v_lshlrev_b64 v[168:169], 11, v[164:165]
	v_exp_f32_e32 v164, v1
	v_and_b32_e32 v1, 0xffff0000, v162
	v_max_f32_e32 v1, 0xc2700000, v1
	v_mul_f32_e32 v1, 0xbfb8aa3b, v1
	v_exp_f32_e32 v165, v1
	v_lshlrev_b32_e32 v1, 16, v163
	v_max_f32_e32 v1, 0xc2700000, v1
	v_mul_f32_e32 v1, 0xbfb8aa3b, v1
	v_exp_f32_e32 v166, v1
	v_and_b32_e32 v1, 0xffff0000, v163
	v_max_f32_e32 v1, 0xc2700000, v1
	v_mul_f32_e32 v1, 0xbfb8aa3b, v1
	v_exp_f32_e32 v167, v1
	v_lshl_add_u64 v[162:163], s[14:15], 0, v[168:169]
	s_mov_b64 s[38:39], -1
	s_and_b64 vcc, exec, s[4:5]
	v_lshl_add_u64 v[162:163], v[2:3], 1, v[162:163]
	s_cbranch_vccnz .LBB0_981
	v_add_f32_e32 v169, 1.0, v167
	v_add_f32_e32 v1, 1.0, v164
	v_add_f32_e32 v145, 1.0, v165
	v_add_f32_e32 v168, 1.0, v166
	v_rcp_f32_e32 v169, v169
	v_rcp_f32_e32 v1, v1
	v_rcp_f32_e32 v145, v145
	v_rcp_f32_e32 v168, v168
	v_mul_f32_e32 v169, v107, v169
	s_mov_b64 s[38:39], 0
	v_mul_f32_e32 v1, v104, v1
	v_mul_f32_e32 v145, v105, v145
	v_mul_f32_e32 v170, v106, v168
	v_cvt_pk_bf16_f32 v168, v1, v145
	v_cvt_pk_bf16_f32 v169, v170, v169
	v_and_b32_e32 v244, 48, v254
	v_mov_b32_e32 v245, 0
	v_lshrrev_b32_e32 v244, 1, v244
	v_mov_b32_e32 v240, v168
	v_mov_b32_e32 v241, v169

; __device__ __forceinline__ unsigned cvt_pk_bf16(float lo, float hi) { unsigned r; asm volatile("v_cvt_pk_bf16_f32 %0, %1, %2" : "=v"(r) : "v"(lo), "v"(hi)); return r; }
;     __device__ __forceinline__ void operator()(f32x4 (&acc)[2][2][4][2], const Unit& u, int wr, int wc, int fr, int fq) const {
;     ...
;                         const unsigned long long wb = wbv[m][bj][n];
;                         f32x4 eb;
;                         eb[0] = __expf(-fmaxf(__uint_as_float((unsigned)(wb & 0xffffull) << 16), -60.f)); eb[1] = __expf(-fmaxf(__uint_as_float((unsigned)((wb >> 16) & 0xffffull) << 16), -60.f));
;                         eb[2] = __expf(-fmaxf(__uint_as_float((unsigned)((wb >> 32) & 0xffffull) << 16), -60.f)); eb[3] = __expf(-fmaxf(__uint_as_float((unsigned)((wb >> 48) & 0xffffull) << 16), -60.f));
;                         if (u.kh == 0) {
;                             const unsigned long long wa = wav[m][bj][n];
;                             f32x4 ea;
;                             ea[0] = __expf(-__uint_as_float((unsigned)(wa & 0xffffull) << 16)); ea[1] = __expf(-__uint_as_float((unsigned)((wa >> 16) & 0xffffull) << 16));
;                             ea[2] = __expf(-__uint_as_float((unsigned)((wa >> 32) & 0xffffull) << 16)); ea[3] = __expf(-__uint_as_float((unsigned)((wa >> 48) & 0xffffull) << 16));
; #pragma unroll
;                             for (int e_ = 0; e_ < 4; ++e_) acc[ai][bj][m][n][e_] *= (1.0f + eb[e_]) * __builtin_amdgcn_rcpf(1.0f + ea[e_]);
;                         } else {
;                             f32x4 o;
; #pragma unroll
;                             for (int e_ = 0; e_ < 4; ++e_) o[e_] = acc[ai][bj][m][n][e_] * __builtin_amdgcn_rcpf(1.0f + eb[e_]);
;                             *(unsigned long long*)(merged + off + bj * HALF + 16 * n) = (unsigned long long)cvt_pk_bf16(o[0], o[1]) | ((unsigned long long)cvt_pk_bf16(o[2], o[3]) << 32);
.LBB0_983:
	v_lshlrev_b32_e32 v1, 16, v158
	v_max_f32_e32 v1, 0xc2700000, v1
	v_mul_f32_e32 v1, 0xbfb8aa3b, v1
	v_exp_f32_e32 v160, v1
	v_and_b32_e32 v1, 0xffff0000, v158
	v_max_f32_e32 v1, 0xc2700000, v1
	v_mul_f32_e32 v1, 0xbfb8aa3b, v1
	v_exp_f32_e32 v161, v1
	v_lshlrev_b32_e32 v1, 16, v159
	v_max_f32_e32 v1, 0xc2700000, v1
	v_mul_f32_e32 v1, 0xbfb8aa3b, v1
	v_exp_f32_e32 v158, v1
	v_and_b32_e32 v1, 0xffff0000, v159
	v_max_f32_e32 v1, 0xc2700000, v1
	v_mul_f32_e32 v1, 0xbfb8aa3b, v1
	v_exp_f32_e32 v159, v1
	s_and_b64 vcc, exec, s[4:5]
	s_mov_b64 s[38:39], -1
	s_cbranch_vccnz .LBB0_985
	v_add_f32_e32 v165, 1.0, v159
	v_add_f32_e32 v1, 1.0, v160
	v_add_f32_e32 v145, 1.0, v161
	v_add_f32_e32 v164, 1.0, v158
	v_rcp_f32_e32 v165, v165
	v_rcp_f32_e32 v1, v1
	v_rcp_f32_e32 v145, v145
	v_rcp_f32_e32 v164, v164
	v_mul_f32_e32 v165, v103, v165
	s_mov_b64 s[38:39], 0
	v_mul_f32_e32 v1, v100, v1
	v_mul_f32_e32 v145, v101, v145
	v_mul_f32_e32 v166, v102, v164
	v_cvt_pk_bf16_f32 v164, v1, v145
	v_cvt_pk_bf16_f32 v165, v166, v165
	v_mov_b32_e32 v242, v164
	v_mov_b32_e32 v243, v165
	v_lshl_add_u64 v[246:247], v[162:163], 0, v[244:245]
	s_nop 0
	v_permlane32_swap_b32_e32 v240, v242
	v_permlane32_swap_b32_e32 v241, v243
	s_nop 0
	v_permlane16_swap_b32_e32 v240, v242
	v_permlane16_swap_b32_e32 v241, v243
	s_nop 1
	global_store_dwordx4 v[246:247], v[240:243], off

; __device__ __forceinline__ unsigned cvt_pk_bf16(float lo, float hi) { unsigned r; asm volatile("v_cvt_pk_bf16_f32 %0, %1, %2" : "=v"(r) : "v"(lo), "v"(hi)); return r; }
;     __device__ __forceinline__ void operator()(f32x4 (&acc)[2][2][4][2], const Unit& u, int wr, int wc, int fr, int fq) const {
;     ...
;                         const unsigned long long wb = wbv[m][bj][n];
;                         f32x4 eb;
;                         eb[0] = __expf(-fmaxf(__uint_as_float((unsigned)(wb & 0xffffull) << 16), -60.f)); eb[1] = __expf(-fmaxf(__uint_as_float((unsigned)((wb >> 16) & 0xffffull) << 16), -60.f));
;                         eb[2] = __expf(-fmaxf(__uint_as_float((unsigned)((wb >> 32) & 0xffffull) << 16), -60.f)); eb[3] = __expf(-fmaxf(__uint_as_float((unsigned)((wb >> 48) & 0xffffull) << 16), -60.f));
;                         if (u.kh == 0) {
;                             const unsigned long long wa = wav[m][bj][n];
;                             f32x4 ea;
;                             ea[0] = __expf(-__uint_as_float((unsigned)(wa & 0xffffull) << 16)); ea[1] = __expf(-__uint_as_float((unsigned)((wa >> 16) & 0xffffull) << 16));
;                             ea[2] = __expf(-__uint_as_float((unsigned)((wa >> 32) & 0xffffull) << 16)); ea[3] = __expf(-__uint_as_float((unsigned)((wa >> 48) & 0xffffull) << 16));
; #pragma unroll
;                             for (int e_ = 0; e_ < 4; ++e_) acc[ai][bj][m][n][e_] *= (1.0f + eb[e_]) * __builtin_amdgcn_rcpf(1.0f + ea[e_]);
;                         } else {
;                             f32x4 o;
; #pragma unroll
;                             for (int e_ = 0; e_ < 4; ++e_) o[e_] = acc[ai][bj][m][n][e_] * __builtin_amdgcn_rcpf(1.0f + eb[e_]);
;                             *(unsigned long long*)(merged + off + bj * HALF + 16 * n) = (unsigned long long)cvt_pk_bf16(o[0], o[1]) | ((unsigned long long)cvt_pk_bf16(o[2], o[3]) << 32);
.LBB0_987:
	v_lshlrev_b32_e32 v1, 16, v154
	v_max_f32_e32 v1, 0xc2700000, v1
	v_mul_f32_e32 v1, 0xbfb8aa3b, v1
	v_exp_f32_e32 v156, v1
	v_and_b32_e32 v1, 0xffff0000, v154
	v_max_f32_e32 v1, 0xc2700000, v1
	v_mul_f32_e32 v1, 0xbfb8aa3b, v1
	v_exp_f32_e32 v157, v1
	v_lshlrev_b32_e32 v1, 16, v155
	v_max_f32_e32 v1, 0xc2700000, v1
	v_mul_f32_e32 v1, 0xbfb8aa3b, v1
	v_exp_f32_e32 v154, v1
	v_and_b32_e32 v1, 0xffff0000, v155
	v_max_f32_e32 v1, 0xc2700000, v1
	v_mul_f32_e32 v1, 0xbfb8aa3b, v1
	v_exp_f32_e32 v155, v1
	s_and_b64 vcc, exec, s[4:5]
	s_mov_b64 s[38:39], -1
	s_cbranch_vccnz .LBB0_989
	v_add_f32_e32 v159, 1.0, v155
	v_add_f32_e32 v1, 1.0, v156
	v_add_f32_e32 v145, 1.0, v157
	v_add_f32_e32 v158, 1.0, v154
	v_rcp_f32_e32 v159, v159
	v_rcp_f32_e32 v1, v1
	v_rcp_f32_e32 v145, v145
	v_rcp_f32_e32 v158, v158
	v_mul_f32_e32 v159, v75, v159
	s_mov_b64 s[38:39], 0
	v_mul_f32_e32 v1, v72, v1
	v_mul_f32_e32 v145, v73, v145
	v_mul_f32_e32 v160, v74, v158
	v_cvt_pk_bf16_f32 v158, v1, v145
	v_cvt_pk_bf16_f32 v159, v160, v159
	v_mov_b32_e32 v240, v158
	v_mov_b32_e32 v241, v159

; __device__ __forceinline__ unsigned cvt_pk_bf16(float lo, float hi) { unsigned r; asm volatile("v_cvt_pk_bf16_f32 %0, %1, %2" : "=v"(r) : "v"(lo), "v"(hi)); return r; }
;     __device__ __forceinline__ void operator()(f32x4 (&acc)[2][2][4][2], const Unit& u, int wr, int wc, int fr, int fq) const {
;     ...
;                         const unsigned long long wb = wbv[m][bj][n];
;                         f32x4 eb;
;                         eb[0] = __expf(-fmaxf(__uint_as_float((unsigned)(wb & 0xffffull) << 16), -60.f)); eb[1] = __expf(-fmaxf(__uint_as_float((unsigned)((wb >> 16) & 0xffffull) << 16), -60.f));
;                         eb[2] = __expf(-fmaxf(__uint_as_float((unsigned)((wb >> 32) & 0xffffull) << 16), -60.f)); eb[3] = __expf(-fmaxf(__uint_as_float((unsigned)((wb >> 48) & 0xffffull) << 16), -60.f));
;                         if (u.kh == 0) {
;                             const unsigned long long wa = wav[m][bj][n];
;                             f32x4 ea;
;                             ea[0] = __expf(-__uint_as_float((unsigned)(wa & 0xffffull) << 16)); ea[1] = __expf(-__uint_as_float((unsigned)((wa >> 16) & 0xffffull) << 16));
;                             ea[2] = __expf(-__uint_as_float((unsigned)((wa >> 32) & 0xffffull) << 16)); ea[3] = __expf(-__uint_as_float((unsigned)((wa >> 48) & 0xffffull) << 16));
; #pragma unroll
;                             for (int e_ = 0; e_ < 4; ++e_) acc[ai][bj][m][n][e_] *= (1.0f + eb[e_]) * __builtin_amdgcn_rcpf(1.0f + ea[e_]);
;                         } else {
;                             f32x4 o;
; #pragma unroll
;                             for (int e_ = 0; e_ < 4; ++e_) o[e_] = acc[ai][bj][m][n][e_] * __builtin_amdgcn_rcpf(1.0f + eb[e_]);
;                             *(unsigned long long*)(merged + off + bj * HALF + 16 * n) = (unsigned long long)cvt_pk_bf16(o[0], o[1]) | ((unsigned long long)cvt_pk_bf16(o[2], o[3]) << 32);
.LBB0_991:
	v_lshlrev_b32_e32 v1, 16, v150
	v_max_f32_e32 v1, 0xc2700000, v1
	v_mul_f32_e32 v1, 0xbfb8aa3b, v1
	v_exp_f32_e32 v152, v1
	v_and_b32_e32 v1, 0xffff0000, v150
	v_max_f32_e32 v1, 0xc2700000, v1
	v_mul_f32_e32 v1, 0xbfb8aa3b, v1
	v_exp_f32_e32 v153, v1
	v_lshlrev_b32_e32 v1, 16, v151
	v_max_f32_e32 v1, 0xc2700000, v1
	v_mul_f32_e32 v1, 0xbfb8aa3b, v1
	v_exp_f32_e32 v150, v1
	v_and_b32_e32 v1, 0xffff0000, v151
	v_max_f32_e32 v1, 0xc2700000, v1
	v_mul_f32_e32 v1, 0xbfb8aa3b, v1
	v_exp_f32_e32 v151, v1
	s_and_b64 vcc, exec, s[4:5]
	s_mov_b64 s[38:39], -1
	s_cbranch_vccnz .LBB0_993
	v_add_f32_e32 v155, 1.0, v151
	v_add_f32_e32 v1, 1.0, v152
	v_add_f32_e32 v145, 1.0, v153
	v_add_f32_e32 v154, 1.0, v150
	v_rcp_f32_e32 v155, v155
	v_rcp_f32_e32 v1, v1
	v_rcp_f32_e32 v145, v145
	v_rcp_f32_e32 v154, v154
	v_mul_f32_e32 v155, v71, v155
	s_mov_b64 s[38:39], 0
	v_mul_f32_e32 v1, v68, v1
	v_mul_f32_e32 v145, v69, v145
	v_mul_f32_e32 v156, v70, v154
	v_cvt_pk_bf16_f32 v154, v1, v145
	v_cvt_pk_bf16_f32 v155, v156, v155
	v_mov_b32_e32 v242, v154
	v_mov_b32_e32 v243, v155
	v_lshl_add_u64 v[246:247], v[162:163], 0, v[244:245]
	s_nop 0
	v_permlane32_swap_b32_e32 v240, v242
	v_permlane32_swap_b32_e32 v241, v243
	s_nop 0
	v_permlane16_swap_b32_e32 v240, v242
	v_permlane16_swap_b32_e32 v241, v243
	s_nop 1
	global_store_dwordx4 v[246:247], v[240:243], off offset:256

; __device__ __forceinline__ unsigned cvt_pk_bf16(float lo, float hi) { unsigned r; asm volatile("v_cvt_pk_bf16_f32 %0, %1, %2" : "=v"(r) : "v"(lo), "v"(hi)); return r; }
;     __device__ __forceinline__ void operator()(f32x4 (&acc)[2][2][4][2], const Unit& u, int wr, int wc, int fr, int fq) const {
;     ...
;                         const unsigned long long wb = wbv[m][bj][n];
;                         f32x4 eb;
;                         eb[0] = __expf(-fmaxf(__uint_as_float((unsigned)(wb & 0xffffull) << 16), -60.f)); eb[1] = __expf(-fmaxf(__uint_as_float((unsigned)((wb >> 16) & 0xffffull) << 16), -60.f));
;                         eb[2] = __expf(-fmaxf(__uint_as_float((unsigned)((wb >> 32) & 0xffffull) << 16), -60.f)); eb[3] = __expf(-fmaxf(__uint_as_float((unsigned)((wb >> 48) & 0xffffull) << 16), -60.f));
;                         if (u.kh == 0) {
;                             const unsigned long long wa = wav[m][bj][n];
;                             f32x4 ea;
;                             ea[0] = __expf(-__uint_as_float((unsigned)(wa & 0xffffull) << 16)); ea[1] = __expf(-__uint_as_float((unsigned)((wa >> 16) & 0xffffull) << 16));
;                             ea[2] = __expf(-__uint_as_float((unsigned)((wa >> 32) & 0xffffull) << 16)); ea[3] = __expf(-__uint_as_float((unsigned)((wa >> 48) & 0xffffull) << 16));
; #pragma unroll
;                             for (int e_ = 0; e_ < 4; ++e_) acc[ai][bj][m][n][e_] *= (1.0f + eb[e_]) * __builtin_amdgcn_rcpf(1.0f + ea[e_]);
;                         } else {
;                             f32x4 o;
; #pragma unroll
;                             for (int e_ = 0; e_ < 4; ++e_) o[e_] = acc[ai][bj][m][n][e_] * __builtin_amdgcn_rcpf(1.0f + eb[e_]);
;                             *(unsigned long long*)(merged + off + bj * HALF + 16 * n) = (unsigned long long)cvt_pk_bf16(o[0], o[1]) | ((unsigned long long)cvt_pk_bf16(o[2], o[3]) << 32);
.LBB0_1011:
	s_waitcnt vmcnt(15)
	v_lshlrev_b32_e32 v1, 16, v208
	v_max_f32_e32 v1, 0xc2700000, v1
	v_mul_f32_e32 v1, 0xbfb8aa3b, v1
	v_lshlrev_b64 v[218:219], 11, v[214:215]
	v_exp_f32_e32 v214, v1
	v_and_b32_e32 v1, 0xffff0000, v208
	v_max_f32_e32 v1, 0xc2700000, v1
	v_mul_f32_e32 v1, 0xbfb8aa3b, v1
	v_exp_f32_e32 v215, v1
	v_lshlrev_b32_e32 v1, 16, v209
	v_max_f32_e32 v1, 0xc2700000, v1
	v_mul_f32_e32 v1, 0xbfb8aa3b, v1
	v_exp_f32_e32 v216, v1
	v_and_b32_e32 v1, 0xffff0000, v209
	v_max_f32_e32 v1, 0xc2700000, v1
	v_mul_f32_e32 v1, 0xbfb8aa3b, v1
	v_exp_f32_e32 v217, v1
	v_lshl_add_u64 v[208:209], s[14:15], 0, v[218:219]
	s_mov_b64 s[6:7], -1
	s_and_b64 vcc, exec, s[4:5]
	v_lshl_add_u64 v[208:209], v[2:3], 1, v[208:209]
	s_cbranch_vccnz .LBB0_1013
	v_add_f32_e32 v218, 1.0, v215
	v_add_f32_e32 v219, 1.0, v216
	v_add_f32_e32 v1, 1.0, v214
	v_rcp_f32_e32 v218, v218
	v_rcp_f32_e32 v219, v219
	v_add_f32_e32 v220, 1.0, v217
	v_rcp_f32_e32 v1, v1
	v_rcp_f32_e32 v220, v220
	v_mul_f32_e32 v218, v65, v218
	v_mul_f32_e32 v219, v66, v219
	s_mov_b64 s[6:7], 0
	v_mul_f32_e32 v1, v64, v1
	v_mul_f32_e32 v220, v67, v220
	v_cvt_pk_bf16_f32 v218, v1, v218
	v_cvt_pk_bf16_f32 v219, v219, v220
	v_and_b32_e32 v244, 48, v254
	v_mov_b32_e32 v245, 0
	v_lshrrev_b32_e32 v244, 1, v244
	v_mov_b32_e32 v240, v218
	v_mov_b32_e32 v241, v219

; __device__ __forceinline__ unsigned cvt_pk_bf16(float lo, float hi) { unsigned r; asm volatile("v_cvt_pk_bf16_f32 %0, %1, %2" : "=v"(r) : "v"(lo), "v"(hi)); return r; }
;     __device__ __forceinline__ void operator()(f32x4 (&acc)[2][2][4][2], const Unit& u, int wr, int wc, int fr, int fq) const {
;     ...
;                         const unsigned long long wb = wbv[m][bj][n];
;                         f32x4 eb;
;                         eb[0] = __expf(-fmaxf(__uint_as_float((unsigned)(wb & 0xffffull) << 16), -60.f)); eb[1] = __expf(-fmaxf(__uint_as_float((unsigned)((wb >> 16) & 0xffffull) << 16), -60.f));
;                         eb[2] = __expf(-fmaxf(__uint_as_float((unsigned)((wb >> 32) & 0xffffull) << 16), -60.f)); eb[3] = __expf(-fmaxf(__uint_as_float((unsigned)((wb >> 48) & 0xffffull) << 16), -60.f));
;                         if (u.kh == 0) {
;                             const unsigned long long wa = wav[m][bj][n];
;                             f32x4 ea;
;                             ea[0] = __expf(-__uint_as_float((unsigned)(wa & 0xffffull) << 16)); ea[1] = __expf(-__uint_as_float((unsigned)((wa >> 16) & 0xffffull) << 16));
;                             ea[2] = __expf(-__uint_as_float((unsigned)((wa >> 32) & 0xffffull) << 16)); ea[3] = __expf(-__uint_as_float((unsigned)((wa >> 48) & 0xffffull) << 16));
; #pragma unroll
;                             for (int e_ = 0; e_ < 4; ++e_) acc[ai][bj][m][n][e_] *= (1.0f + eb[e_]) * __builtin_amdgcn_rcpf(1.0f + ea[e_]);
;                         } else {
;                             f32x4 o;
; #pragma unroll
;                             for (int e_ = 0; e_ < 4; ++e_) o[e_] = acc[ai][bj][m][n][e_] * __builtin_amdgcn_rcpf(1.0f + eb[e_]);
;                             *(unsigned long long*)(merged + off + bj * HALF + 16 * n) = (unsigned long long)cvt_pk_bf16(o[0], o[1]) | ((unsigned long long)cvt_pk_bf16(o[2], o[3]) << 32);
.LBB0_1015:
	s_waitcnt vmcnt(14)
	v_lshlrev_b32_e32 v1, 16, v210
	v_max_f32_e32 v1, 0xc2700000, v1
	v_mul_f32_e32 v1, 0xbfb8aa3b, v1
	v_exp_f32_e32 v212, v1
	v_and_b32_e32 v1, 0xffff0000, v210
	v_max_f32_e32 v1, 0xc2700000, v1
	v_mul_f32_e32 v1, 0xbfb8aa3b, v1
	v_exp_f32_e32 v213, v1
	v_lshlrev_b32_e32 v1, 16, v211
	v_max_f32_e32 v1, 0xc2700000, v1
	v_mul_f32_e32 v1, 0xbfb8aa3b, v1
	v_exp_f32_e32 v210, v1
	v_and_b32_e32 v1, 0xffff0000, v211
	v_max_f32_e32 v1, 0xc2700000, v1
	v_mul_f32_e32 v1, 0xbfb8aa3b, v1
	v_exp_f32_e32 v211, v1
	s_and_b64 vcc, exec, s[4:5]
	s_mov_b64 s[6:7], -1
	s_cbranch_vccnz .LBB0_1017
	v_add_f32_e32 v214, 1.0, v213
	v_add_f32_e32 v215, 1.0, v210
	v_add_f32_e32 v1, 1.0, v212
	v_rcp_f32_e32 v214, v214
	v_rcp_f32_e32 v215, v215
	v_add_f32_e32 v216, 1.0, v211
	v_rcp_f32_e32 v1, v1
	v_rcp_f32_e32 v216, v216
	v_mul_f32_e32 v214, v61, v214
	v_mul_f32_e32 v215, v62, v215
	s_mov_b64 s[6:7], 0
	v_mul_f32_e32 v1, v60, v1
	v_mul_f32_e32 v216, v63, v216
	v_cvt_pk_bf16_f32 v214, v1, v214
	v_cvt_pk_bf16_f32 v215, v215, v216
	v_mov_b32_e32 v242, v214
	v_mov_b32_e32 v243, v215
	v_lshl_add_u64 v[246:247], v[208:209], 0, v[244:245]
	s_nop 0
	v_permlane32_swap_b32_e32 v240, v242
	v_permlane32_swap_b32_e32 v241, v243
	s_nop 0
	v_permlane16_swap_b32_e32 v240, v242
	v_permlane16_swap_b32_e32 v241, v243
	s_nop 1
	global_store_dwordx4 v[246:247], v[240:243], off

; __device__ __forceinline__ unsigned cvt_pk_bf16(float lo, float hi) { unsigned r; asm volatile("v_cvt_pk_bf16_f32 %0, %1, %2" : "=v"(r) : "v"(lo), "v"(hi)); return r; }
;     __device__ __forceinline__ void operator()(f32x4 (&acc)[2][2][4][2], const Unit& u, int wr, int wc, int fr, int fq) const {
;     ...
;                         const unsigned long long wb = wbv[m][bj][n];
;                         f32x4 eb;
;                         eb[0] = __expf(-fmaxf(__uint_as_float((unsigned)(wb & 0xffffull) << 16), -60.f)); eb[1] = __expf(-fmaxf(__uint_as_float((unsigned)((wb >> 16) & 0xffffull) << 16), -60.f));
;                         eb[2] = __expf(-fmaxf(__uint_as_float((unsigned)((wb >> 32) & 0xffffull) << 16), -60.f)); eb[3] = __expf(-fmaxf(__uint_as_float((unsigned)((wb >> 48) & 0xffffull) << 16), -60.f));
;     ...
;                             f32x4 o;
; #pragma unroll
;                             for (int e_ = 0; e_ < 4; ++e_) o[e_] = acc[ai][bj][m][n][e_] * __builtin_amdgcn_rcpf(1.0f + eb[e_]);
;                             *(unsigned long long*)(merged + off + bj * HALF + 16 * n) = (unsigned long long)cvt_pk_bf16(o[0], o[1]) | ((unsigned long long)cvt_pk_bf16(o[2], o[3]) << 32);
.LBB0_1019:
	s_waitcnt vmcnt(13)
	v_lshlrev_b32_e32 v1, 16, v204
	v_max_f32_e32 v1, 0xc2700000, v1
	v_mul_f32_e32 v1, 0xbfb8aa3b, v1
	v_exp_f32_e32 v206, v1
	v_and_b32_e32 v1, 0xffff0000, v204
	v_max_f32_e32 v1, 0xc2700000, v1
	v_mul_f32_e32 v1, 0xbfb8aa3b, v1
	v_exp_f32_e32 v207, v1
	v_lshlrev_b32_e32 v1, 16, v205
	v_max_f32_e32 v1, 0xc2700000, v1
	v_mul_f32_e32 v1, 0xbfb8aa3b, v1
	v_exp_f32_e32 v204, v1
	v_and_b32_e32 v1, 0xffff0000, v205
	v_max_f32_e32 v1, 0xc2700000, v1
	v_mul_f32_e32 v1, 0xbfb8aa3b, v1
	v_exp_f32_e32 v205, v1
	s_and_b64 vcc, exec, s[4:5]
	s_mov_b64 s[6:7], -1
	s_cbranch_vccnz .LBB0_1021
	v_add_f32_e32 v210, 1.0, v207
	v_add_f32_e32 v211, 1.0, v204
	v_add_f32_e32 v1, 1.0, v206
	v_rcp_f32_e32 v210, v210
	v_rcp_f32_e32 v211, v211
	v_add_f32_e32 v212, 1.0, v205
	v_rcp_f32_e32 v1, v1
	v_rcp_f32_e32 v212, v212
	v_mul_f32_e32 v210, v33, v210
	v_mul_f32_e32 v211, v34, v211
	s_mov_b64 s[6:7], 0
	v_mul_f32_e32 v1, v32, v1
	v_mul_f32_e32 v212, v35, v212
	v_cvt_pk_bf16_f32 v210, v1, v210
	v_cvt_pk_bf16_f32 v211, v211, v212
	v_mov_b32_e32 v240, v210
	v_mov_b32_e32 v241, v211

; __device__ __forceinline__ unsigned cvt_pk_bf16(float lo, float hi) { unsigned r; asm volatile("v_cvt_pk_bf16_f32 %0, %1, %2" : "=v"(r) : "v"(lo), "v"(hi)); return r; }
;     __device__ __forceinline__ void operator()(f32x4 (&acc)[2][2][4][2], const Unit& u, int wr, int wc, int fr, int fq) const {
;     ...
;                         const unsigned long long wb = wbv[m][bj][n];
;                         f32x4 eb;
;                         eb[0] = __expf(-fmaxf(__uint_as_float((unsigned)(wb & 0xffffull) << 16), -60.f)); eb[1] = __expf(-fmaxf(__uint_as_float((unsigned)((wb >> 16) & 0xffffull) << 16), -60.f));
;                         eb[2] = __expf(-fmaxf(__uint_as_float((unsigned)((wb >> 32) & 0xffffull) << 16), -60.f)); eb[3] = __expf(-fmaxf(__uint_as_float((unsigned)((wb >> 48) & 0xffffull) << 16), -60.f));
;     ...
;                             f32x4 o;
; #pragma unroll
;                             for (int e_ = 0; e_ < 4; ++e_) o[e_] = acc[ai][bj][m][n][e_] * __builtin_amdgcn_rcpf(1.0f + eb[e_]);
;                             *(unsigned long long*)(merged + off + bj * HALF + 16 * n) = (unsigned long long)cvt_pk_bf16(o[0], o[1]) | ((unsigned long long)cvt_pk_bf16(o[2], o[3]) << 32);
.LBB0_1023:
	s_waitcnt vmcnt(12)
	v_lshlrev_b32_e32 v1, 16, v200
	v_max_f32_e32 v1, 0xc2700000, v1
	v_mul_f32_e32 v1, 0xbfb8aa3b, v1
	v_exp_f32_e32 v202, v1
	v_and_b32_e32 v1, 0xffff0000, v200
	v_max_f32_e32 v1, 0xc2700000, v1
	v_mul_f32_e32 v1, 0xbfb8aa3b, v1
	v_exp_f32_e32 v203, v1
	v_lshlrev_b32_e32 v1, 16, v201
	v_max_f32_e32 v1, 0xc2700000, v1
	v_mul_f32_e32 v1, 0xbfb8aa3b, v1
	v_exp_f32_e32 v200, v1
	v_and_b32_e32 v1, 0xffff0000, v201
	v_max_f32_e32 v1, 0xc2700000, v1
	v_mul_f32_e32 v1, 0xbfb8aa3b, v1
	v_exp_f32_e32 v201, v1
	s_and_b64 vcc, exec, s[4:5]
	s_mov_b64 s[6:7], -1
	s_cbranch_vccnz .LBB0_1025
	v_add_f32_e32 v204, 1.0, v203
	v_add_f32_e32 v205, 1.0, v200
	v_add_f32_e32 v1, 1.0, v202
	v_rcp_f32_e32 v204, v204
	v_rcp_f32_e32 v205, v205
	v_add_f32_e32 v206, 1.0, v201
	v_rcp_f32_e32 v1, v1
	v_rcp_f32_e32 v206, v206
	v_mul_f32_e32 v204, v29, v204
	v_mul_f32_e32 v205, v30, v205
	s_mov_b64 s[6:7], 0
	v_mul_f32_e32 v1, v28, v1
	v_mul_f32_e32 v206, v31, v206
	v_cvt_pk_bf16_f32 v204, v1, v204
	v_cvt_pk_bf16_f32 v205, v205, v206
	v_mov_b32_e32 v242, v204
	v_mov_b32_e32 v243, v205
	v_lshl_add_u64 v[246:247], v[208:209], 0, v[244:245]
	s_nop 0
	v_permlane32_swap_b32_e32 v240, v242
	v_permlane32_swap_b32_e32 v241, v243
	s_nop 0
	v_permlane16_swap_b32_e32 v240, v242
	v_permlane16_swap_b32_e32 v241, v243
	s_nop 1
	global_store_dwordx4 v[246:247], v[240:243], off offset:256

; __device__ __forceinline__ unsigned cvt_pk_bf16(float lo, float hi) { unsigned r; asm volatile("v_cvt_pk_bf16_f32 %0, %1, %2" : "=v"(r) : "v"(lo), "v"(hi)); return r; }
;     __device__ __forceinline__ void operator()(f32x4 (&acc)[2][2][4][2], const Unit& u, int wr, int wc, int fr, int fq) const {
;     ...
;                         const unsigned long long wb = wbv[m][bj][n];
;                         f32x4 eb;
;                         eb[0] = __expf(-fmaxf(__uint_as_float((unsigned)(wb & 0xffffull) << 16), -60.f)); eb[1] = __expf(-fmaxf(__uint_as_float((unsigned)((wb >> 16) & 0xffffull) << 16), -60.f));
;                         eb[2] = __expf(-fmaxf(__uint_as_float((unsigned)((wb >> 32) & 0xffffull) << 16), -60.f)); eb[3] = __expf(-fmaxf(__uint_as_float((unsigned)((wb >> 48) & 0xffffull) << 16), -60.f));
;     ...
;                             f32x4 o;
; #pragma unroll
;                             for (int e_ = 0; e_ < 4; ++e_) o[e_] = acc[ai][bj][m][n][e_] * __builtin_amdgcn_rcpf(1.0f + eb[e_]);
;                             *(unsigned long long*)(merged + off + bj * HALF + 16 * n) = (unsigned long long)cvt_pk_bf16(o[0], o[1]) | ((unsigned long long)cvt_pk_bf16(o[2], o[3]) << 32);
.LBB0_1027:
	s_waitcnt vmcnt(11)
	v_lshlrev_b32_e32 v1, 16, v194
	v_max_f32_e32 v1, 0xc2700000, v1
	v_mul_f32_e32 v1, 0xbfb8aa3b, v1
	v_lshlrev_b64 v[200:201], 11, v[196:197]
	v_exp_f32_e32 v196, v1
	v_and_b32_e32 v1, 0xffff0000, v194
	v_max_f32_e32 v1, 0xc2700000, v1
	v_mul_f32_e32 v1, 0xbfb8aa3b, v1
	v_exp_f32_e32 v197, v1
	v_lshlrev_b32_e32 v1, 16, v195
	v_max_f32_e32 v1, 0xc2700000, v1
	v_mul_f32_e32 v1, 0xbfb8aa3b, v1
	v_exp_f32_e32 v198, v1
	v_and_b32_e32 v1, 0xffff0000, v195
	v_max_f32_e32 v1, 0xc2700000, v1
	v_mul_f32_e32 v1, 0xbfb8aa3b, v1
	v_exp_f32_e32 v199, v1
	v_lshl_add_u64 v[194:195], s[14:15], 0, v[200:201]
	s_mov_b64 s[6:7], -1
	s_and_b64 vcc, exec, s[4:5]
	v_lshl_add_u64 v[194:195], v[2:3], 1, v[194:195]
	s_cbranch_vccnz .LBB0_1029
	v_add_f32_e32 v200, 1.0, v197
	v_add_f32_e32 v201, 1.0, v198
	v_add_f32_e32 v1, 1.0, v196
	v_rcp_f32_e32 v200, v200
	v_rcp_f32_e32 v201, v201
	v_add_f32_e32 v202, 1.0, v199
	v_rcp_f32_e32 v1, v1
	v_rcp_f32_e32 v202, v202
	v_mul_f32_e32 v200, v57, v200
	v_mul_f32_e32 v201, v58, v201
	s_mov_b64 s[6:7], 0
	v_mul_f32_e32 v1, v56, v1
	v_mul_f32_e32 v202, v59, v202
	v_cvt_pk_bf16_f32 v200, v1, v200
	v_cvt_pk_bf16_f32 v201, v201, v202
	v_and_b32_e32 v244, 48, v254
	v_mov_b32_e32 v245, 0
	v_lshrrev_b32_e32 v244, 1, v244
	v_mov_b32_e32 v240, v200
	v_mov_b32_e32 v241, v201

; __device__ __forceinline__ unsigned cvt_pk_bf16(float lo, float hi) { unsigned r; asm volatile("v_cvt_pk_bf16_f32 %0, %1, %2" : "=v"(r) : "v"(lo), "v"(hi)); return r; }
;     __device__ __forceinline__ void operator()(f32x4 (&acc)[2][2][4][2], const Unit& u, int wr, int wc, int fr, int fq) const {
;     ...
;                         const unsigned long long wb = wbv[m][bj][n];
;                         f32x4 eb;
;                         eb[0] = __expf(-fmaxf(__uint_as_float((unsigned)(wb & 0xffffull) << 16), -60.f)); eb[1] = __expf(-fmaxf(__uint_as_float((unsigned)((wb >> 16) & 0xffffull) << 16), -60.f));
;                         eb[2] = __expf(-fmaxf(__uint_as_float((unsigned)((wb >> 32) & 0xffffull) << 16), -60.f)); eb[3] = __expf(-fmaxf(__uint_as_float((unsigned)((wb >> 48) & 0xffffull) << 16), -60.f));
;     ...
;                             f32x4 o;
; #pragma unroll
;                             for (int e_ = 0; e_ < 4; ++e_) o[e_] = acc[ai][bj][m][n][e_] * __builtin_amdgcn_rcpf(1.0f + eb[e_]);
;                             *(unsigned long long*)(merged + off + bj * HALF + 16 * n) = (unsigned long long)cvt_pk_bf16(o[0], o[1]) | ((unsigned long long)cvt_pk_bf16(o[2], o[3]) << 32);
.LBB0_1031:
	s_waitcnt vmcnt(10)
	v_lshlrev_b32_e32 v1, 16, v190
	v_max_f32_e32 v1, 0xc2700000, v1
	v_mul_f32_e32 v1, 0xbfb8aa3b, v1
	v_exp_f32_e32 v192, v1
	v_and_b32_e32 v1, 0xffff0000, v190
	v_max_f32_e32 v1, 0xc2700000, v1
	v_mul_f32_e32 v1, 0xbfb8aa3b, v1
	v_exp_f32_e32 v193, v1
	v_lshlrev_b32_e32 v1, 16, v191
	v_max_f32_e32 v1, 0xc2700000, v1
	v_mul_f32_e32 v1, 0xbfb8aa3b, v1
	v_exp_f32_e32 v190, v1
	v_and_b32_e32 v1, 0xffff0000, v191
	v_max_f32_e32 v1, 0xc2700000, v1
	v_mul_f32_e32 v1, 0xbfb8aa3b, v1
	v_exp_f32_e32 v191, v1
	s_and_b64 vcc, exec, s[4:5]
	s_mov_b64 s[6:7], -1
	s_cbranch_vccnz .LBB0_1033
	v_add_f32_e32 v196, 1.0, v193
	v_add_f32_e32 v197, 1.0, v190
	v_add_f32_e32 v1, 1.0, v192
	v_rcp_f32_e32 v196, v196
	v_rcp_f32_e32 v197, v197
	v_add_f32_e32 v198, 1.0, v191
	v_rcp_f32_e32 v1, v1
	v_rcp_f32_e32 v198, v198
	v_mul_f32_e32 v196, v53, v196
	v_mul_f32_e32 v197, v54, v197
	s_mov_b64 s[6:7], 0
	v_mul_f32_e32 v1, v52, v1
	v_mul_f32_e32 v198, v55, v198
	v_cvt_pk_bf16_f32 v196, v1, v196
	v_cvt_pk_bf16_f32 v197, v197, v198
	v_mov_b32_e32 v242, v196
	v_mov_b32_e32 v243, v197
	v_lshl_add_u64 v[246:247], v[194:195], 0, v[244:245]
	s_nop 0
	v_permlane32_swap_b32_e32 v240, v242
	v_permlane32_swap_b32_e32 v241, v243
	s_nop 0
	v_permlane16_swap_b32_e32 v240, v242
	v_permlane16_swap_b32_e32 v241, v243
	s_nop 1
	global_store_dwordx4 v[246:247], v[240:243], off

; __device__ __forceinline__ unsigned cvt_pk_bf16(float lo, float hi) { unsigned r; asm volatile("v_cvt_pk_bf16_f32 %0, %1, %2" : "=v"(r) : "v"(lo), "v"(hi)); return r; }
;     __device__ __forceinline__ void operator()(f32x4 (&acc)[2][2][4][2], const Unit& u, int wr, int wc, int fr, int fq) const {
;     ...
;                         const unsigned long long wb = wbv[m][bj][n];
;                         f32x4 eb;
;                         eb[0] = __expf(-fmaxf(__uint_as_float((unsigned)(wb & 0xffffull) << 16), -60.f)); eb[1] = __expf(-fmaxf(__uint_as_float((unsigned)((wb >> 16) & 0xffffull) << 16), -60.f));
;                         eb[2] = __expf(-fmaxf(__uint_as_float((unsigned)((wb >> 32) & 0xffffull) << 16), -60.f)); eb[3] = __expf(-fmaxf(__uint_as_float((unsigned)((wb >> 48) & 0xffffull) << 16), -60.f));
;     ...
;                             f32x4 o;
; #pragma unroll
;                             for (int e_ = 0; e_ < 4; ++e_) o[e_] = acc[ai][bj][m][n][e_] * __builtin_amdgcn_rcpf(1.0f + eb[e_]);
;                             *(unsigned long long*)(merged + off + bj * HALF + 16 * n) = (unsigned long long)cvt_pk_bf16(o[0], o[1]) | ((unsigned long long)cvt_pk_bf16(o[2], o[3]) << 32);
.LBB0_1035:
	s_waitcnt vmcnt(9)
	v_lshlrev_b32_e32 v1, 16, v186
	v_max_f32_e32 v1, 0xc2700000, v1
	v_mul_f32_e32 v1, 0xbfb8aa3b, v1
	v_exp_f32_e32 v188, v1
	v_and_b32_e32 v1, 0xffff0000, v186
	v_max_f32_e32 v1, 0xc2700000, v1
	v_mul_f32_e32 v1, 0xbfb8aa3b, v1
	v_exp_f32_e32 v189, v1
	v_lshlrev_b32_e32 v1, 16, v187
	v_max_f32_e32 v1, 0xc2700000, v1
	v_mul_f32_e32 v1, 0xbfb8aa3b, v1
	v_exp_f32_e32 v186, v1
	v_and_b32_e32 v1, 0xffff0000, v187
	v_max_f32_e32 v1, 0xc2700000, v1
	v_mul_f32_e32 v1, 0xbfb8aa3b, v1
	v_exp_f32_e32 v187, v1
	s_and_b64 vcc, exec, s[4:5]
	s_mov_b64 s[6:7], -1
	s_cbranch_vccnz .LBB0_1037
	v_add_f32_e32 v190, 1.0, v189
	v_add_f32_e32 v191, 1.0, v186
	v_add_f32_e32 v1, 1.0, v188
	v_rcp_f32_e32 v190, v190
	v_rcp_f32_e32 v191, v191
	v_add_f32_e32 v192, 1.0, v187
	v_rcp_f32_e32 v1, v1
	v_rcp_f32_e32 v192, v192
	v_mul_f32_e32 v190, v25, v190
	v_mul_f32_e32 v191, v26, v191
	s_mov_b64 s[6:7], 0
	v_mul_f32_e32 v1, v24, v1
	v_mul_f32_e32 v192, v27, v192
	v_cvt_pk_bf16_f32 v190, v1, v190
	v_cvt_pk_bf16_f32 v191, v191, v192
	v_mov_b32_e32 v240, v190
	v_mov_b32_e32 v241, v191

; __device__ __forceinline__ unsigned cvt_pk_bf16(float lo, float hi) { unsigned r; asm volatile("v_cvt_pk_bf16_f32 %0, %1, %2" : "=v"(r) : "v"(lo), "v"(hi)); return r; }
;     __device__ __forceinline__ void operator()(f32x4 (&acc)[2][2][4][2], const Unit& u, int wr, int wc, int fr, int fq) const {
;     ...
;                         const unsigned long long wb = wbv[m][bj][n];
;                         f32x4 eb;
;                         eb[0] = __expf(-fmaxf(__uint_as_float((unsigned)(wb & 0xffffull) << 16), -60.f)); eb[1] = __expf(-fmaxf(__uint_as_float((unsigned)((wb >> 16) & 0xffffull) << 16), -60.f));
;                         eb[2] = __expf(-fmaxf(__uint_as_float((unsigned)((wb >> 32) & 0xffffull) << 16), -60.f)); eb[3] = __expf(-fmaxf(__uint_as_float((unsigned)((wb >> 48) & 0xffffull) << 16), -60.f));
;     ...
;                             f32x4 o;
; #pragma unroll
;                             for (int e_ = 0; e_ < 4; ++e_) o[e_] = acc[ai][bj][m][n][e_] * __builtin_amdgcn_rcpf(1.0f + eb[e_]);
;                             *(unsigned long long*)(merged + off + bj * HALF + 16 * n) = (unsigned long long)cvt_pk_bf16(o[0], o[1]) | ((unsigned long long)cvt_pk_bf16(o[2], o[3]) << 32);
.LBB0_1039:
	s_waitcnt vmcnt(8)
	v_lshlrev_b32_e32 v1, 16, v182
	v_max_f32_e32 v1, 0xc2700000, v1
	v_mul_f32_e32 v1, 0xbfb8aa3b, v1
	v_exp_f32_e32 v184, v1
	v_and_b32_e32 v1, 0xffff0000, v182
	v_max_f32_e32 v1, 0xc2700000, v1
	v_mul_f32_e32 v1, 0xbfb8aa3b, v1
	v_exp_f32_e32 v185, v1
	v_lshlrev_b32_e32 v1, 16, v183
	v_max_f32_e32 v1, 0xc2700000, v1
	v_mul_f32_e32 v1, 0xbfb8aa3b, v1
	v_exp_f32_e32 v182, v1
	v_and_b32_e32 v1, 0xffff0000, v183
	v_max_f32_e32 v1, 0xc2700000, v1
	v_mul_f32_e32 v1, 0xbfb8aa3b, v1
	v_exp_f32_e32 v183, v1
	s_and_b64 vcc, exec, s[4:5]
	s_mov_b64 s[6:7], -1
	s_cbranch_vccnz .LBB0_1041
	v_add_f32_e32 v186, 1.0, v185
	v_add_f32_e32 v187, 1.0, v182
	v_add_f32_e32 v1, 1.0, v184
	v_rcp_f32_e32 v186, v186
	v_rcp_f32_e32 v187, v187
	v_add_f32_e32 v188, 1.0, v183
	v_rcp_f32_e32 v1, v1
	v_rcp_f32_e32 v188, v188
	v_mul_f32_e32 v186, v21, v186
	v_mul_f32_e32 v187, v22, v187
	s_mov_b64 s[6:7], 0
	v_mul_f32_e32 v1, v20, v1
	v_mul_f32_e32 v188, v23, v188
	v_cvt_pk_bf16_f32 v186, v1, v186
	v_cvt_pk_bf16_f32 v187, v187, v188
	v_mov_b32_e32 v242, v186
	v_mov_b32_e32 v243, v187
	v_lshl_add_u64 v[246:247], v[194:195], 0, v[244:245]
	s_nop 0
	v_permlane32_swap_b32_e32 v240, v242
	v_permlane32_swap_b32_e32 v241, v243
	s_nop 0
	v_permlane16_swap_b32_e32 v240, v242
	v_permlane16_swap_b32_e32 v241, v243
	s_nop 1
	global_store_dwordx4 v[246:247], v[240:243], off offset:256

; __device__ __forceinline__ unsigned cvt_pk_bf16(float lo, float hi) { unsigned r; asm volatile("v_cvt_pk_bf16_f32 %0, %1, %2" : "=v"(r) : "v"(lo), "v"(hi)); return r; }
;     __device__ __forceinline__ void operator()(f32x4 (&acc)[2][2][4][2], const Unit& u, int wr, int wc, int fr, int fq) const {
;     ...
;                         const unsigned long long wb = wbv[m][bj][n];
;                         f32x4 eb;
;                         eb[0] = __expf(-fmaxf(__uint_as_float((unsigned)(wb & 0xffffull) << 16), -60.f)); eb[1] = __expf(-fmaxf(__uint_as_float((unsigned)((wb >> 16) & 0xffffull) << 16), -60.f));
;                         eb[2] = __expf(-fmaxf(__uint_as_float((unsigned)((wb >> 32) & 0xffffull) << 16), -60.f)); eb[3] = __expf(-fmaxf(__uint_as_float((unsigned)((wb >> 48) & 0xffffull) << 16), -60.f));
;     ...
;                             f32x4 o;
; #pragma unroll
;                             for (int e_ = 0; e_ < 4; ++e_) o[e_] = acc[ai][bj][m][n][e_] * __builtin_amdgcn_rcpf(1.0f + eb[e_]);
;                             *(unsigned long long*)(merged + off + bj * HALF + 16 * n) = (unsigned long long)cvt_pk_bf16(o[0], o[1]) | ((unsigned long long)cvt_pk_bf16(o[2], o[3]) << 32);
.LBB0_1043:
	s_waitcnt vmcnt(7)
	v_lshlrev_b32_e32 v1, 16, v176
	v_max_f32_e32 v1, 0xc2700000, v1
	v_mul_f32_e32 v1, 0xbfb8aa3b, v1
	v_lshlrev_b64 v[182:183], 11, v[178:179]
	v_exp_f32_e32 v178, v1
	v_and_b32_e32 v1, 0xffff0000, v176
	v_max_f32_e32 v1, 0xc2700000, v1
	v_mul_f32_e32 v1, 0xbfb8aa3b, v1
	v_exp_f32_e32 v179, v1
	v_lshlrev_b32_e32 v1, 16, v177
	v_max_f32_e32 v1, 0xc2700000, v1
	v_mul_f32_e32 v1, 0xbfb8aa3b, v1
	v_exp_f32_e32 v180, v1
	v_and_b32_e32 v1, 0xffff0000, v177
	v_max_f32_e32 v1, 0xc2700000, v1
	v_mul_f32_e32 v1, 0xbfb8aa3b, v1
	v_exp_f32_e32 v181, v1
	v_lshl_add_u64 v[176:177], s[14:15], 0, v[182:183]
	s_mov_b64 s[6:7], -1
	s_and_b64 vcc, exec, s[4:5]
	v_lshl_add_u64 v[176:177], v[2:3], 1, v[176:177]
	s_cbranch_vccnz .LBB0_1045
	v_add_f32_e32 v182, 1.0, v179
	v_add_f32_e32 v183, 1.0, v180
	v_add_f32_e32 v1, 1.0, v178
	v_rcp_f32_e32 v182, v182
	v_rcp_f32_e32 v183, v183
	v_add_f32_e32 v184, 1.0, v181
	v_rcp_f32_e32 v1, v1
	v_rcp_f32_e32 v184, v184
	v_mul_f32_e32 v182, v49, v182
	v_mul_f32_e32 v183, v50, v183
	s_mov_b64 s[6:7], 0
	v_mul_f32_e32 v1, v48, v1
	v_mul_f32_e32 v184, v51, v184
	v_cvt_pk_bf16_f32 v182, v1, v182
	v_cvt_pk_bf16_f32 v183, v183, v184
	v_and_b32_e32 v244, 48, v254
	v_mov_b32_e32 v245, 0
	v_lshrrev_b32_e32 v244, 1, v244
	v_mov_b32_e32 v240, v182
	v_mov_b32_e32 v241, v183

; __device__ __forceinline__ unsigned cvt_pk_bf16(float lo, float hi) { unsigned r; asm volatile("v_cvt_pk_bf16_f32 %0, %1, %2" : "=v"(r) : "v"(lo), "v"(hi)); return r; }
;     __device__ __forceinline__ void operator()(f32x4 (&acc)[2][2][4][2], const Unit& u, int wr, int wc, int fr, int fq) const {
;     ...
;                         const unsigned long long wb = wbv[m][bj][n];
;                         f32x4 eb;
;                         eb[0] = __expf(-fmaxf(__uint_as_float((unsigned)(wb & 0xffffull) << 16), -60.f)); eb[1] = __expf(-fmaxf(__uint_as_float((unsigned)((wb >> 16) & 0xffffull) << 16), -60.f));
;                         eb[2] = __expf(-fmaxf(__uint_as_float((unsigned)((wb >> 32) & 0xffffull) << 16), -60.f)); eb[3] = __expf(-fmaxf(__uint_as_float((unsigned)((wb >> 48) & 0xffffull) << 16), -60.f));
;     ...
;                             f32x4 o;
; #pragma unroll
;                             for (int e_ = 0; e_ < 4; ++e_) o[e_] = acc[ai][bj][m][n][e_] * __builtin_amdgcn_rcpf(1.0f + eb[e_]);
;                             *(unsigned long long*)(merged + off + bj * HALF + 16 * n) = (unsigned long long)cvt_pk_bf16(o[0], o[1]) | ((unsigned long long)cvt_pk_bf16(o[2], o[3]) << 32);
.LBB0_1047:
	s_waitcnt vmcnt(6)
	v_lshlrev_b32_e32 v1, 16, v172
	v_max_f32_e32 v1, 0xc2700000, v1
	v_mul_f32_e32 v1, 0xbfb8aa3b, v1
	v_exp_f32_e32 v174, v1
	v_and_b32_e32 v1, 0xffff0000, v172
	v_max_f32_e32 v1, 0xc2700000, v1
	v_mul_f32_e32 v1, 0xbfb8aa3b, v1
	v_exp_f32_e32 v175, v1
	v_lshlrev_b32_e32 v1, 16, v173
	v_max_f32_e32 v1, 0xc2700000, v1
	v_mul_f32_e32 v1, 0xbfb8aa3b, v1
	v_exp_f32_e32 v172, v1
	v_and_b32_e32 v1, 0xffff0000, v173
	v_max_f32_e32 v1, 0xc2700000, v1
	v_mul_f32_e32 v1, 0xbfb8aa3b, v1
	v_exp_f32_e32 v173, v1
	s_and_b64 vcc, exec, s[4:5]
	s_mov_b64 s[6:7], -1
	s_cbranch_vccnz .LBB0_1049
	v_add_f32_e32 v178, 1.0, v175
	v_add_f32_e32 v179, 1.0, v172
	v_add_f32_e32 v1, 1.0, v174
	v_rcp_f32_e32 v178, v178
	v_rcp_f32_e32 v179, v179
	v_add_f32_e32 v180, 1.0, v173
	v_rcp_f32_e32 v1, v1
	v_rcp_f32_e32 v180, v180
	v_mul_f32_e32 v178, v45, v178
	v_mul_f32_e32 v179, v46, v179
	s_mov_b64 s[6:7], 0
	v_mul_f32_e32 v1, v44, v1
	v_mul_f32_e32 v180, v47, v180
	v_cvt_pk_bf16_f32 v178, v1, v178
	v_cvt_pk_bf16_f32 v179, v179, v180
	v_mov_b32_e32 v242, v178
	v_mov_b32_e32 v243, v179
	v_lshl_add_u64 v[246:247], v[176:177], 0, v[244:245]
	s_nop 0
	v_permlane32_swap_b32_e32 v240, v242
	v_permlane32_swap_b32_e32 v241, v243
	s_nop 0
	v_permlane16_swap_b32_e32 v240, v242
	v_permlane16_swap_b32_e32 v241, v243
	s_nop 1
	global_store_dwordx4 v[246:247], v[240:243], off

; __device__ __forceinline__ unsigned cvt_pk_bf16(float lo, float hi) { unsigned r; asm volatile("v_cvt_pk_bf16_f32 %0, %1, %2" : "=v"(r) : "v"(lo), "v"(hi)); return r; }
;     __device__ __forceinline__ void operator()(f32x4 (&acc)[2][2][4][2], const Unit& u, int wr, int wc, int fr, int fq) const {
;     ...
;                         const unsigned long long wb = wbv[m][bj][n];
;                         f32x4 eb;
;                         eb[0] = __expf(-fmaxf(__uint_as_float((unsigned)(wb & 0xffffull) << 16), -60.f)); eb[1] = __expf(-fmaxf(__uint_as_float((unsigned)((wb >> 16) & 0xffffull) << 16), -60.f));
;                         eb[2] = __expf(-fmaxf(__uint_as_float((unsigned)((wb >> 32) & 0xffffull) << 16), -60.f)); eb[3] = __expf(-fmaxf(__uint_as_float((unsigned)((wb >> 48) & 0xffffull) << 16), -60.f));
;     ...
;                             f32x4 o;
; #pragma unroll
;                             for (int e_ = 0; e_ < 4; ++e_) o[e_] = acc[ai][bj][m][n][e_] * __builtin_amdgcn_rcpf(1.0f + eb[e_]);
;                             *(unsigned long long*)(merged + off + bj * HALF + 16 * n) = (unsigned long long)cvt_pk_bf16(o[0], o[1]) | ((unsigned long long)cvt_pk_bf16(o[2], o[3]) << 32);
.LBB0_1051:
	s_waitcnt vmcnt(5)
	v_lshlrev_b32_e32 v1, 16, v168
	v_max_f32_e32 v1, 0xc2700000, v1
	v_mul_f32_e32 v1, 0xbfb8aa3b, v1
	v_exp_f32_e32 v170, v1
	v_and_b32_e32 v1, 0xffff0000, v168
	v_max_f32_e32 v1, 0xc2700000, v1
	v_mul_f32_e32 v1, 0xbfb8aa3b, v1
	v_exp_f32_e32 v171, v1
	v_lshlrev_b32_e32 v1, 16, v169
	v_max_f32_e32 v1, 0xc2700000, v1
	v_mul_f32_e32 v1, 0xbfb8aa3b, v1
	v_exp_f32_e32 v168, v1
	v_and_b32_e32 v1, 0xffff0000, v169
	v_max_f32_e32 v1, 0xc2700000, v1
	v_mul_f32_e32 v1, 0xbfb8aa3b, v1
	v_exp_f32_e32 v169, v1
	s_and_b64 vcc, exec, s[4:5]
	s_mov_b64 s[6:7], -1
	s_cbranch_vccnz .LBB0_1053
	v_add_f32_e32 v172, 1.0, v171
	v_add_f32_e32 v173, 1.0, v168
	v_add_f32_e32 v1, 1.0, v170
	v_rcp_f32_e32 v172, v172
	v_rcp_f32_e32 v173, v173
	v_add_f32_e32 v174, 1.0, v169
	v_rcp_f32_e32 v1, v1
	v_rcp_f32_e32 v174, v174
	v_mul_f32_e32 v172, v17, v172
	v_mul_f32_e32 v173, v18, v173
	s_mov_b64 s[6:7], 0
	v_mul_f32_e32 v1, v16, v1
	v_mul_f32_e32 v174, v19, v174
	v_cvt_pk_bf16_f32 v172, v1, v172
	v_cvt_pk_bf16_f32 v173, v173, v174
	v_mov_b32_e32 v240, v172
	v_mov_b32_e32 v241, v173

; __device__ __forceinline__ unsigned cvt_pk_bf16(float lo, float hi) { unsigned r; asm volatile("v_cvt_pk_bf16_f32 %0, %1, %2" : "=v"(r) : "v"(lo), "v"(hi)); return r; }
;     __device__ __forceinline__ void operator()(f32x4 (&acc)[2][2][4][2], const Unit& u, int wr, int wc, int fr, int fq) const {
;     ...
;                         const unsigned long long wb = wbv[m][bj][n];
;                         f32x4 eb;
;                         eb[0] = __expf(-fmaxf(__uint_as_float((unsigned)(wb & 0xffffull) << 16), -60.f)); eb[1] = __expf(-fmaxf(__uint_as_float((unsigned)((wb >> 16) & 0xffffull) << 16), -60.f));
;                         eb[2] = __expf(-fmaxf(__uint_as_float((unsigned)((wb >> 32) & 0xffffull) << 16), -60.f)); eb[3] = __expf(-fmaxf(__uint_as_float((unsigned)((wb >> 48) & 0xffffull) << 16), -60.f));
;     ...
;                             f32x4 o;
; #pragma unroll
;                             for (int e_ = 0; e_ < 4; ++e_) o[e_] = acc[ai][bj][m][n][e_] * __builtin_amdgcn_rcpf(1.0f + eb[e_]);
;                             *(unsigned long long*)(merged + off + bj * HALF + 16 * n) = (unsigned long long)cvt_pk_bf16(o[0], o[1]) | ((unsigned long long)cvt_pk_bf16(o[2], o[3]) << 32);
.LBB0_1055:
	s_waitcnt vmcnt(4)
	v_lshlrev_b32_e32 v1, 16, v164
	v_max_f32_e32 v1, 0xc2700000, v1
	v_mul_f32_e32 v1, 0xbfb8aa3b, v1
	v_exp_f32_e32 v166, v1
	v_and_b32_e32 v1, 0xffff0000, v164
	v_max_f32_e32 v1, 0xc2700000, v1
	v_mul_f32_e32 v1, 0xbfb8aa3b, v1
	v_exp_f32_e32 v167, v1
	v_lshlrev_b32_e32 v1, 16, v165
	v_max_f32_e32 v1, 0xc2700000, v1
	v_mul_f32_e32 v1, 0xbfb8aa3b, v1
	v_exp_f32_e32 v164, v1
	v_and_b32_e32 v1, 0xffff0000, v165
	v_max_f32_e32 v1, 0xc2700000, v1
	v_mul_f32_e32 v1, 0xbfb8aa3b, v1
	v_exp_f32_e32 v165, v1
	s_and_b64 vcc, exec, s[4:5]
	s_mov_b64 s[6:7], -1
	s_cbranch_vccnz .LBB0_1057
	v_add_f32_e32 v168, 1.0, v167
	v_add_f32_e32 v169, 1.0, v164
	v_add_f32_e32 v1, 1.0, v166
	v_rcp_f32_e32 v168, v168
	v_rcp_f32_e32 v169, v169
	v_add_f32_e32 v170, 1.0, v165
	v_rcp_f32_e32 v1, v1
	v_rcp_f32_e32 v170, v170
	v_mul_f32_e32 v168, v13, v168
	v_mul_f32_e32 v169, v14, v169
	s_mov_b64 s[6:7], 0
	v_mul_f32_e32 v1, v12, v1
	v_mul_f32_e32 v170, v15, v170
	v_cvt_pk_bf16_f32 v168, v1, v168
	v_cvt_pk_bf16_f32 v169, v169, v170
	v_mov_b32_e32 v242, v168
	v_mov_b32_e32 v243, v169
	v_lshl_add_u64 v[246:247], v[176:177], 0, v[244:245]
	s_nop 0
	v_permlane32_swap_b32_e32 v240, v242
	v_permlane32_swap_b32_e32 v241, v243
	s_nop 0
	v_permlane16_swap_b32_e32 v240, v242
	v_permlane16_swap_b32_e32 v241, v243
	s_nop 1
	global_store_dwordx4 v[246:247], v[240:243], off offset:256

; __device__ __forceinline__ unsigned cvt_pk_bf16(float lo, float hi) { unsigned r; asm volatile("v_cvt_pk_bf16_f32 %0, %1, %2" : "=v"(r) : "v"(lo), "v"(hi)); return r; }
;     __device__ __forceinline__ void operator()(f32x4 (&acc)[2][2][4][2], const Unit& u, int wr, int wc, int fr, int fq) const {
;     ...
;                         const unsigned long long wb = wbv[m][bj][n];
;                         f32x4 eb;
;                         eb[0] = __expf(-fmaxf(__uint_as_float((unsigned)(wb & 0xffffull) << 16), -60.f)); eb[1] = __expf(-fmaxf(__uint_as_float((unsigned)((wb >> 16) & 0xffffull) << 16), -60.f));
;                         eb[2] = __expf(-fmaxf(__uint_as_float((unsigned)((wb >> 32) & 0xffffull) << 16), -60.f)); eb[3] = __expf(-fmaxf(__uint_as_float((unsigned)((wb >> 48) & 0xffffull) << 16), -60.f));
;     ...
;                             f32x4 o;
; #pragma unroll
;                             for (int e_ = 0; e_ < 4; ++e_) o[e_] = acc[ai][bj][m][n][e_] * __builtin_amdgcn_rcpf(1.0f + eb[e_]);
;                             *(unsigned long long*)(merged + off + bj * HALF + 16 * n) = (unsigned long long)cvt_pk_bf16(o[0], o[1]) | ((unsigned long long)cvt_pk_bf16(o[2], o[3]) << 32);
.LBB0_1059:
	s_waitcnt vmcnt(3)
	v_lshlrev_b32_e32 v1, 16, v158
	v_max_f32_e32 v1, 0xc2700000, v1
	v_mul_f32_e32 v1, 0xbfb8aa3b, v1
	v_lshlrev_b64 v[162:163], 11, v[160:161]
	v_exp_f32_e32 v160, v1
	v_and_b32_e32 v1, 0xffff0000, v158
	v_max_f32_e32 v1, 0xc2700000, v1
	v_mul_f32_e32 v1, 0xbfb8aa3b, v1
	v_exp_f32_e32 v161, v1
	v_lshlrev_b32_e32 v1, 16, v159
	v_max_f32_e32 v1, 0xc2700000, v1
	v_mul_f32_e32 v1, 0xbfb8aa3b, v1
	v_exp_f32_e32 v158, v1
	v_and_b32_e32 v1, 0xffff0000, v159
	v_max_f32_e32 v1, 0xc2700000, v1
	v_mul_f32_e32 v1, 0xbfb8aa3b, v1
	v_exp_f32_e32 v159, v1
	v_lshl_add_u64 v[162:163], s[14:15], 0, v[162:163]
	s_mov_b64 s[6:7], -1
	s_and_b64 vcc, exec, s[4:5]
	v_lshl_add_u64 v[2:3], v[2:3], 1, v[162:163]
	s_cbranch_vccnz .LBB0_1061
	v_add_f32_e32 v162, 1.0, v161
	v_add_f32_e32 v163, 1.0, v158
	v_add_f32_e32 v1, 1.0, v160
	v_rcp_f32_e32 v162, v162
	v_rcp_f32_e32 v163, v163
	v_add_f32_e32 v164, 1.0, v159
	v_rcp_f32_e32 v1, v1
	v_rcp_f32_e32 v164, v164
	v_mul_f32_e32 v162, v41, v162
	v_mul_f32_e32 v163, v42, v163
	s_mov_b64 s[6:7], 0
	v_mul_f32_e32 v1, v40, v1
	v_mul_f32_e32 v164, v43, v164
	v_cvt_pk_bf16_f32 v162, v1, v162
	v_cvt_pk_bf16_f32 v163, v163, v164
	v_and_b32_e32 v244, 48, v254
	v_mov_b32_e32 v245, 0
	v_lshrrev_b32_e32 v244, 1, v244
	v_mov_b32_e32 v240, v162
	v_mov_b32_e32 v241, v163

; __device__ __forceinline__ unsigned cvt_pk_bf16(float lo, float hi) { unsigned r; asm volatile("v_cvt_pk_bf16_f32 %0, %1, %2" : "=v"(r) : "v"(lo), "v"(hi)); return r; }
;     __device__ __forceinline__ void operator()(f32x4 (&acc)[2][2][4][2], const Unit& u, int wr, int wc, int fr, int fq) const {
;     ...
;                         const unsigned long long wb = wbv[m][bj][n];
;                         f32x4 eb;
;                         eb[0] = __expf(-fmaxf(__uint_as_float((unsigned)(wb & 0xffffull) << 16), -60.f)); eb[1] = __expf(-fmaxf(__uint_as_float((unsigned)((wb >> 16) & 0xffffull) << 16), -60.f));
;                         eb[2] = __expf(-fmaxf(__uint_as_float((unsigned)((wb >> 32) & 0xffffull) << 16), -60.f)); eb[3] = __expf(-fmaxf(__uint_as_float((unsigned)((wb >> 48) & 0xffffull) << 16), -60.f));
;     ...
;                             f32x4 o;
; #pragma unroll
;                             for (int e_ = 0; e_ < 4; ++e_) o[e_] = acc[ai][bj][m][n][e_] * __builtin_amdgcn_rcpf(1.0f + eb[e_]);
;                             *(unsigned long long*)(merged + off + bj * HALF + 16 * n) = (unsigned long long)cvt_pk_bf16(o[0], o[1]) | ((unsigned long long)cvt_pk_bf16(o[2], o[3]) << 32);
.LBB0_1063:
	s_waitcnt vmcnt(2)
	v_lshlrev_b32_e32 v1, 16, v154
	v_max_f32_e32 v1, 0xc2700000, v1
	v_mul_f32_e32 v1, 0xbfb8aa3b, v1
	v_exp_f32_e32 v156, v1
	v_and_b32_e32 v1, 0xffff0000, v154
	v_max_f32_e32 v1, 0xc2700000, v1
	v_mul_f32_e32 v1, 0xbfb8aa3b, v1
	v_exp_f32_e32 v157, v1
	v_lshlrev_b32_e32 v1, 16, v155
	v_max_f32_e32 v1, 0xc2700000, v1
	v_mul_f32_e32 v1, 0xbfb8aa3b, v1
	v_exp_f32_e32 v154, v1
	v_and_b32_e32 v1, 0xffff0000, v155
	v_max_f32_e32 v1, 0xc2700000, v1
	v_mul_f32_e32 v1, 0xbfb8aa3b, v1
	v_exp_f32_e32 v155, v1
	s_and_b64 vcc, exec, s[4:5]
	s_mov_b64 s[6:7], -1
	s_cbranch_vccnz .LBB0_1065
	v_add_f32_e32 v158, 1.0, v157
	v_add_f32_e32 v159, 1.0, v154
	v_add_f32_e32 v1, 1.0, v156
	v_rcp_f32_e32 v158, v158
	v_rcp_f32_e32 v159, v159
	v_add_f32_e32 v160, 1.0, v155
	v_rcp_f32_e32 v1, v1
	v_rcp_f32_e32 v160, v160
	v_mul_f32_e32 v158, v37, v158
	v_mul_f32_e32 v159, v38, v159
	s_mov_b64 s[6:7], 0
	v_mul_f32_e32 v1, v36, v1
	v_mul_f32_e32 v160, v39, v160
	v_cvt_pk_bf16_f32 v158, v1, v158
	v_cvt_pk_bf16_f32 v159, v159, v160
	v_mov_b32_e32 v242, v158
	v_mov_b32_e32 v243, v159
	v_lshl_add_u64 v[246:247], v[2:3], 0, v[244:245]
	s_nop 0
	v_permlane32_swap_b32_e32 v240, v242
	v_permlane32_swap_b32_e32 v241, v243
	s_nop 0
	v_permlane16_swap_b32_e32 v240, v242
	v_permlane16_swap_b32_e32 v241, v243
	s_nop 1
	global_store_dwordx4 v[246:247], v[240:243], off

; __device__ __forceinline__ unsigned cvt_pk_bf16(float lo, float hi) { unsigned r; asm volatile("v_cvt_pk_bf16_f32 %0, %1, %2" : "=v"(r) : "v"(lo), "v"(hi)); return r; }
;     __device__ __forceinline__ void operator()(f32x4 (&acc)[2][2][4][2], const Unit& u, int wr, int wc, int fr, int fq) const {
;     ...
;                         const unsigned long long wb = wbv[m][bj][n];
;                         f32x4 eb;
;                         eb[0] = __expf(-fmaxf(__uint_as_float((unsigned)(wb & 0xffffull) << 16), -60.f)); eb[1] = __expf(-fmaxf(__uint_as_float((unsigned)((wb >> 16) & 0xffffull) << 16), -60.f));
;                         eb[2] = __expf(-fmaxf(__uint_as_float((unsigned)((wb >> 32) & 0xffffull) << 16), -60.f)); eb[3] = __expf(-fmaxf(__uint_as_float((unsigned)((wb >> 48) & 0xffffull) << 16), -60.f));
;     ...
;                             f32x4 o;
; #pragma unroll
;                             for (int e_ = 0; e_ < 4; ++e_) o[e_] = acc[ai][bj][m][n][e_] * __builtin_amdgcn_rcpf(1.0f + eb[e_]);
;                             *(unsigned long long*)(merged + off + bj * HALF + 16 * n) = (unsigned long long)cvt_pk_bf16(o[0], o[1]) | ((unsigned long long)cvt_pk_bf16(o[2], o[3]) << 32);
.LBB0_1067:
	s_waitcnt vmcnt(1)
	v_lshlrev_b32_e32 v1, 16, v150
	v_max_f32_e32 v1, 0xc2700000, v1
	v_mul_f32_e32 v1, 0xbfb8aa3b, v1
	v_exp_f32_e32 v152, v1
	v_and_b32_e32 v1, 0xffff0000, v150
	v_max_f32_e32 v1, 0xc2700000, v1
	v_mul_f32_e32 v1, 0xbfb8aa3b, v1
	v_exp_f32_e32 v153, v1
	v_lshlrev_b32_e32 v1, 16, v151
	v_max_f32_e32 v1, 0xc2700000, v1
	v_mul_f32_e32 v1, 0xbfb8aa3b, v1
	v_exp_f32_e32 v150, v1
	v_and_b32_e32 v1, 0xffff0000, v151
	v_max_f32_e32 v1, 0xc2700000, v1
	v_mul_f32_e32 v1, 0xbfb8aa3b, v1
	v_exp_f32_e32 v151, v1
	s_and_b64 vcc, exec, s[4:5]
	s_mov_b64 s[6:7], -1
	s_cbranch_vccnz .LBB0_1069
	v_add_f32_e32 v154, 1.0, v153
	v_add_f32_e32 v155, 1.0, v150
	v_add_f32_e32 v1, 1.0, v152
	v_rcp_f32_e32 v154, v154
	v_rcp_f32_e32 v155, v155
	v_add_f32_e32 v156, 1.0, v151
	v_rcp_f32_e32 v1, v1
	v_rcp_f32_e32 v156, v156
	v_mul_f32_e32 v154, v9, v154
	v_mul_f32_e32 v155, v10, v155
	s_mov_b64 s[6:7], 0
	v_mul_f32_e32 v1, v8, v1
	v_mul_f32_e32 v156, v11, v156
	v_cvt_pk_bf16_f32 v154, v1, v154
	v_cvt_pk_bf16_f32 v155, v155, v156
	v_mov_b32_e32 v240, v154
	v_mov_b32_e32 v241, v155

; __device__ __forceinline__ unsigned cvt_pk_bf16(float lo, float hi) { unsigned r; asm volatile("v_cvt_pk_bf16_f32 %0, %1, %2" : "=v"(r) : "v"(lo), "v"(hi)); return r; }
;     __device__ __forceinline__ void operator()(f32x4 (&acc)[2][2][4][2], const Unit& u, int wr, int wc, int fr, int fq) const {
;     ...
;                         const unsigned long long wb = wbv[m][bj][n];
;                         f32x4 eb;
;                         eb[0] = __expf(-fmaxf(__uint_as_float((unsigned)(wb & 0xffffull) << 16), -60.f)); eb[1] = __expf(-fmaxf(__uint_as_float((unsigned)((wb >> 16) & 0xffffull) << 16), -60.f));
;                         eb[2] = __expf(-fmaxf(__uint_as_float((unsigned)((wb >> 32) & 0xffffull) << 16), -60.f)); eb[3] = __expf(-fmaxf(__uint_as_float((unsigned)((wb >> 48) & 0xffffull) << 16), -60.f));
;     ...
;                             f32x4 o;
; #pragma unroll
;                             for (int e_ = 0; e_ < 4; ++e_) o[e_] = acc[ai][bj][m][n][e_] * __builtin_amdgcn_rcpf(1.0f + eb[e_]);
;                             *(unsigned long long*)(merged + off + bj * HALF + 16 * n) = (unsigned long long)cvt_pk_bf16(o[0], o[1]) | ((unsigned long long)cvt_pk_bf16(o[2], o[3]) << 32);
.LBB0_1071:
	s_waitcnt vmcnt(0)
	v_lshlrev_b32_e32 v1, 16, v146
	v_max_f32_e32 v1, 0xc2700000, v1
	v_mul_f32_e32 v1, 0xbfb8aa3b, v1
	v_exp_f32_e32 v148, v1
	v_and_b32_e32 v1, 0xffff0000, v146
	v_max_f32_e32 v1, 0xc2700000, v1
	v_mul_f32_e32 v1, 0xbfb8aa3b, v1
	v_exp_f32_e32 v149, v1
	v_lshlrev_b32_e32 v1, 16, v147
	v_max_f32_e32 v1, 0xc2700000, v1
	v_mul_f32_e32 v1, 0xbfb8aa3b, v1
	v_exp_f32_e32 v146, v1
	v_and_b32_e32 v1, 0xffff0000, v147
	v_max_f32_e32 v1, 0xc2700000, v1
	v_mul_f32_e32 v1, 0xbfb8aa3b, v1
	v_exp_f32_e32 v147, v1
	s_and_b64 vcc, exec, s[4:5]
	s_mov_b64 s[4:5], -1
	s_cbranch_vccnz .LBB0_1074
	v_add_f32_e32 v150, 1.0, v149
	v_add_f32_e32 v151, 1.0, v146
	v_add_f32_e32 v1, 1.0, v148
	v_rcp_f32_e32 v150, v150
	v_rcp_f32_e32 v151, v151
	v_add_f32_e32 v152, 1.0, v147
	v_rcp_f32_e32 v1, v1
	v_rcp_f32_e32 v152, v152
	v_mul_f32_e32 v150, v5, v150
	v_mul_f32_e32 v151, v6, v151
	v_mul_f32_e32 v1, v4, v1
	v_mul_f32_e32 v152, v7, v152
	v_cvt_pk_bf16_f32 v150, v1, v150
	v_cvt_pk_bf16_f32 v151, v151, v152
	v_mov_b32_e32 v242, v150
	v_mov_b32_e32 v243, v151
	v_lshl_add_u64 v[246:247], v[2:3], 0, v[244:245]
	s_nop 0
	v_permlane32_swap_b32_e32 v240, v242
	v_permlane32_swap_b32_e32 v241, v243
	s_nop 0
	v_permlane16_swap_b32_e32 v240, v242
	v_permlane16_swap_b32_e32 v241, v243
	s_nop 1
	global_store_dwordx4 v[246:247], v[240:243], off offset:256
	s_cbranch_execz .LBB0_1075
